# static priority raise for the younger wave half extended to all five GEMM K-loops (set at loop entry, cleared at exit)
# speedup vs baseline: 1.0048x; 1.0048x over previous
; #define PG8_STAGE(bufoff, gbase, voff) do { _Pragma("unroll") for (int _i = 0; _i < 2; ++_i) \
;         __builtin_amdgcn_global_load_lds((const unsigned*)((const char*)(gbase) + (voff)[_i]), (LAS unsigned*)(lds + (bufoff) + ldsw + _i * 8192), 16, 0, 0); } while (0)
; #define PG8_LDA(dst, b, h) do { _Pragma("unroll") for (int m = 0; m < 4; ++m) _Pragma("unroll") for (int k = 0; k < 2; ++k) dst[m][k] = *(const LAS bf16x8*)(lds + PG8_SA(b, h) + aoff + m * 2048 + k * 1024); } while (0)
; #define PG8_LDB(dst, b, h) do { _Pragma("unroll") for (int n = 0; n < 2; ++n) _Pragma("unroll") for (int k = 0; k < 2; ++k) dst[n][k] = *(const LAS bf16x8*)(lds + PG8_SB(b, h) + boff + n * 2048 + k * 1024); } while (0)
; #define PG8_MMA(ai, bj, At, Bt) do { __builtin_amdgcn_s_setprio(1); _Pragma("unroll") for (int m = 0; m < 4; ++m) _Pragma("unroll") for (int n = 0; n < 2; ++n) _Pragma("unroll") for (int k = 0; k < 2; ++k) \
;         acc[ai][bj][m][n] = __builtin_amdgcn_mfma_f32_16x16x32_bf16(Bt[n][k], At[m][k], acc[ai][bj][m][n], 0, 0, 0); __builtin_amdgcn_s_setprio(0); } while (0)
; #define PG8_WAIT_V(n) asm volatile("s_waitcnt vmcnt(" #n ")" ::: "memory")
; #define PG8_WAIT_L(n) asm volatile("s_waitcnt lgkmcnt(" #n ")" ::: "memory")
; #define PG8_BAR __builtin_amdgcn_s_barrier()
; #define PG8_SCHED __builtin_amdgcn_sched_barrier(0)
; template <class Epi, class Sched>
; __device__ __forceinline__ void gemm_phase(LAS unsigned char* lds, const Gemm g, const Sched& S, const Epi& E) {
;     ...
;         const bool has_next = S.next(ui + 1, nxt);
;         const char* nA = has_next ? (const char*)g.A + (size_t)nxt.pm * tstepA + (size_t)nxt.pn * apn : cA; const char* nB = has_next ? (const char*)g.Bt + (size_t)nxt.pn * tstepB : cB;
;         for (int t = 0; t < nt; t += 2) {
;             const bool last = (t == nt - 2);
;             const char* a1 = cA + (size_t)(t + 1) * kstep;
;             const char* a2 = last ? nA : cA + (size_t)(t + 2) * kstep; const char* b2 = last ? nB : cB + (size_t)(t + 2) * kstep;
;             const char* a3 = a2 + kstep; const char* b3 = b2 + kstep;
;             PG8_LDB(B0, 0, 0); PG8_LDB(B1, 0, 1); PG8_SCHED; PG8_LDA(At, 0, 0); PG8_STAGE(PG8_SA(1, 1), a1 + hstepA, voffA);
;             PG8_WAIT_V(8); PG8_WAIT_L(0); PG8_BAR; PG8_MMA(0, 0, At, B0); PG8_MMA(0, 1, At, B1); PG8_BAR; PG8_SCHED;
.LBB0_95:
	s_ashr_i32 s13, s12, 31
	s_lshl_b64 s[6:7], s[12:13], 19
	s_add_u32 s46, s84, s6
	s_addc_u32 s47, s85, s7
	s_and_b64 s[6:7], s[50:51], exec
	s_cselect_b32 s13, s47, s43
	s_cselect_b32 s57, s46, s42
	s_ashr_i32 s45, s44, 31
	s_lshl_b64 s[6:7], s[44:45], 19
	s_add_u32 s48, s8, s6
	s_addc_u32 s49, s9, s7
	s_and_b64 s[6:7], s[50:51], exec
	s_cselect_b32 s45, s49, s53
	s_cselect_b32 s68, s48, s52
	s_add_u32 s42, s42, 0x40080
	s_addc_u32 s43, s43, 0
	s_add_u32 s52, s52, 0x100
	s_addc_u32 s53, s53, 0
	s_mov_b32 s69, -2
	s_cmp_eq_u64 s[18:19], 0
	s_cbranch_scc0 .Lprio_96
	s_setprio 1
.Lprio_96:
	s_cmp_eq_u32 s40, 12
	s_cselect_b32 s101, 1, 0
	s_cmp_eq_u64 s[22:23], 0
	s_cselect_b32 s100, s101, 0
	s_add_u32 s0, s42, 0xfffc0080
	s_addc_u32 s6, s43, -1
	s_add_i32 s26, 0, 0x10000
	s_cmp_eq_u32 s69, 12
	s_cselect_b32 s15, s13, s6
	s_cselect_b32 s14, s57, s0
	v_add_u32_e32 v152, s26, v156
	s_cselect_b32 s7, s45, s53
	s_cselect_b32 s6, s68, s52
	s_add_i32 s0, 0, 0x14000
	ds_read_b128 v[144:147], v152
	ds_read_b128 v[148:151], v152 offset:1024
	ds_read_b128 v[164:167], v152 offset:2048
	ds_read_b128 v[168:171], v152 offset:3072
	v_add_u32_e32 v152, s0, v156
	ds_read_b128 v[172:175], v152
	ds_read_b128 v[190:193], v152 offset:1024
	ds_read_b128 v[196:199], v152 offset:2048
	ds_read_b128 v[200:203], v152 offset:3072
	v_lshl_add_u64 v[152:153], s[42:43], 0, v[140:141]
	s_add_i32 m0, s21, 0xc000
	ds_read_b128 v[204:207], v162
	ds_read_b128 v[208:211], v162 offset:1024
	ds_read_b128 v[212:215], v162 offset:2048
	ds_read_b128 v[216:219], v162 offset:3072
	ds_read_b128 v[220:223], v162 offset:4096
	ds_read_b128 v[224:227], v162 offset:5120
	ds_read_b128 v[228:231], v162 offset:6144
	ds_read_b128 v[232:235], v162 offset:7168
	global_load_lds_dwordx4 v[152:153], off
	v_lshl_add_u64 v[152:153], s[42:43], 0, v[142:143]
	s_add_i32 m0, s21, 0xe000
	s_nop 0
	global_load_lds_dwordx4 v[152:153], off
	s_cmp_lg_u32 s101, 0
	s_waitcnt vmcnt(8)
	s_waitcnt lgkmcnt(0)
	s_barrier
	s_waitcnt lgkmcnt(0)
	s_cbranch_scc1 .Lgt_p_0
	v_mfma_f32_16x16x32_bf16 v[128:131], v[144:147], v[204:207], 0
	v_mfma_f32_16x16x32_bf16 v[124:127], v[164:167], v[204:207], 0
	v_mfma_f32_16x16x32_bf16 v[120:123], v[144:147], v[212:215], 0
	v_mfma_f32_16x16x32_bf16 v[108:111], v[164:167], v[212:215], 0
	v_mfma_f32_16x16x32_bf16 v[104:107], v[144:147], v[220:223], 0
	v_mfma_f32_16x16x32_bf16 v[92:95], v[164:167], v[220:223], 0
	v_mfma_f32_16x16x32_bf16 v[88:91], v[144:147], v[228:231], 0
	v_mfma_f32_16x16x32_bf16 v[76:79], v[164:167], v[228:231], 0
	v_mfma_f32_16x16x32_bf16 v[128:131], v[148:151], v[208:211], v[128:131]
	v_mfma_f32_16x16x32_bf16 v[124:127], v[168:171], v[208:211], v[124:127]
	v_mfma_f32_16x16x32_bf16 v[120:123], v[148:151], v[216:219], v[120:123]
	v_mfma_f32_16x16x32_bf16 v[108:111], v[168:171], v[216:219], v[108:111]
	v_mfma_f32_16x16x32_bf16 v[104:107], v[148:151], v[224:227], v[104:107]
	v_mfma_f32_16x16x32_bf16 v[92:95], v[168:171], v[224:227], v[92:95]
	v_mfma_f32_16x16x32_bf16 v[88:91], v[148:151], v[232:235], v[88:91]
	v_mfma_f32_16x16x32_bf16 v[76:79], v[168:171], v[232:235], v[76:79]
	v_mfma_f32_16x16x32_bf16 v[116:119], v[172:175], v[204:207], 0
	v_mfma_f32_16x16x32_bf16 v[112:115], v[196:199], v[204:207], 0
	v_mfma_f32_16x16x32_bf16 v[100:103], v[172:175], v[212:215], 0
	v_mfma_f32_16x16x32_bf16 v[96:99], v[196:199], v[212:215], 0
	v_mfma_f32_16x16x32_bf16 v[84:87], v[172:175], v[220:223], 0
	v_mfma_f32_16x16x32_bf16 v[80:83], v[196:199], v[220:223], 0
	v_mfma_f32_16x16x32_bf16 v[72:75], v[172:175], v[228:231], 0
	v_mfma_f32_16x16x32_bf16 v[68:71], v[196:199], v[228:231], 0
	v_mfma_f32_16x16x32_bf16 v[116:119], v[190:193], v[208:211], v[116:119]
	v_mfma_f32_16x16x32_bf16 v[112:115], v[200:203], v[208:211], v[112:115]
	v_mfma_f32_16x16x32_bf16 v[100:103], v[190:193], v[216:219], v[100:103]
	v_mfma_f32_16x16x32_bf16 v[96:99], v[200:203], v[216:219], v[96:99]
	v_mfma_f32_16x16x32_bf16 v[84:87], v[190:193], v[224:227], v[84:87]
	v_mfma_f32_16x16x32_bf16 v[80:83], v[200:203], v[224:227], v[80:83]
	v_mfma_f32_16x16x32_bf16 v[72:75], v[190:193], v[232:235], v[72:75]
	v_mfma_f32_16x16x32_bf16 v[68:71], v[200:203], v[232:235], v[68:71]

; #define PG8_MMA(ai, bj, At, Bt) do { __builtin_amdgcn_s_setprio(1); _Pragma("unroll") for (int m = 0; m < 4; ++m) _Pragma("unroll") for (int n = 0; n < 2; ++n) _Pragma("unroll") for (int k = 0; k < 2; ++k) \
;         acc[ai][bj][m][n] = __builtin_amdgcn_mfma_f32_16x16x32_bf16(Bt[n][k], At[m][k], acc[ai][bj][m][n], 0, 0, 0); __builtin_amdgcn_s_setprio(0); } while (0)
; #define PG8_WAIT_V(n) asm volatile("s_waitcnt vmcnt(" #n ")" ::: "memory")
; #define PG8_WAIT_L(n) asm volatile("s_waitcnt lgkmcnt(" #n ")" ::: "memory")
; #define PG8_BAR __builtin_amdgcn_s_barrier()
; #define PG8_SCHED __builtin_amdgcn_sched_barrier(0)
; template <class Epi, class Sched>
; __device__ __forceinline__ void gemm_phase(LAS unsigned char* lds, const Gemm g, const Sched& S, const Epi& E) {
;     ...
;             PG8_WAIT_V(8); PG8_WAIT_L(0); PG8_BAR; PG8_MMA(1, 0, At, B0); PG8_MMA(1, 1, At, B1); PG8_BAR; PG8_SCHED;
;         }
;         if (wr == 0) PG8_BAR;
.Lgt_l_3_done:
	s_barrier
	s_add_i32 s69, s69, 2
	s_add_u32 s42, s42, 0x100
	s_addc_u32 s43, s43, 0
	s_add_u32 s52, s52, 0x100
	s_addc_u32 s53, s53, 0
	s_cmp_gt_u32 s69, 13
	s_cbranch_scc0 .LBB0_96
	s_setprio 0
	s_and_b64 vcc, exec, s[18:19]
	s_cbranch_vccz .LBB0_99
	s_barrier

; #define PG8_STAGE(bufoff, gbase, voff) do { _Pragma("unroll") for (int _i = 0; _i < 2; ++_i) \
;         __builtin_amdgcn_global_load_lds((const unsigned*)((const char*)(gbase) + (voff)[_i]), (LAS unsigned*)(lds + (bufoff) + ldsw + _i * 8192), 16, 0, 0); } while (0)
; #define PG8_LDA(dst, b, h) do { _Pragma("unroll") for (int m = 0; m < 4; ++m) _Pragma("unroll") for (int k = 0; k < 2; ++k) dst[m][k] = *(const LAS bf16x8*)(lds + PG8_SA(b, h) + aoff + m * 2048 + k * 1024); } while (0)
; #define PG8_LDB(dst, b, h) do { _Pragma("unroll") for (int n = 0; n < 2; ++n) _Pragma("unroll") for (int k = 0; k < 2; ++k) dst[n][k] = *(const LAS bf16x8*)(lds + PG8_SB(b, h) + boff + n * 2048 + k * 1024); } while (0)
; #define PG8_MMA(ai, bj, At, Bt) do { __builtin_amdgcn_s_setprio(1); _Pragma("unroll") for (int m = 0; m < 4; ++m) _Pragma("unroll") for (int n = 0; n < 2; ++n) _Pragma("unroll") for (int k = 0; k < 2; ++k) \
;         acc[ai][bj][m][n] = __builtin_amdgcn_mfma_f32_16x16x32_bf16(Bt[n][k], At[m][k], acc[ai][bj][m][n], 0, 0, 0); __builtin_amdgcn_s_setprio(0); } while (0)
; #define PG8_BAR __builtin_amdgcn_s_barrier()
; template <class Epi, class Sched>
; __device__ __forceinline__ void gemm_phase(LAS unsigned char* lds, const Gemm g, const Sched& S, const Epi& E) {
;     ...
;         const bool has_next = S.next(ui + 1, nxt);
;         const char* nA = has_next ? (const char*)g.A + (size_t)nxt.pm * tstepA + (size_t)nxt.pn * apn : cA; const char* nB = has_next ? (const char*)g.Bt + (size_t)nxt.pn * tstepB : cB;
;         for (int t = 0; t < nt; t += 2) {
;             const bool last = (t == nt - 2);
;             const char* a1 = cA + (size_t)(t + 1) * kstep;
;             const char* a2 = last ? nA : cA + (size_t)(t + 2) * kstep; const char* b2 = last ? nB : cB + (size_t)(t + 2) * kstep;
;             const char* a3 = a2 + kstep; const char* b3 = b2 + kstep;
;             PG8_LDB(B0, 0, 0); PG8_LDB(B1, 0, 1); PG8_SCHED; PG8_LDA(At, 0, 0); PG8_STAGE(PG8_SA(1, 1), a1 + hstepA, voffA);
;             PG8_WAIT_V(8); PG8_WAIT_L(0); PG8_BAR; PG8_MMA(0, 0, At, B0); PG8_MMA(0, 1, At, B1); PG8_BAR; PG8_SCHED;
;             PG8_LDA(At, 0, 1); PG8_STAGE(PG8_SB(0, 0), b2, voffB); PG8_STAGE(PG8_SB(0, 1), b2 + hstepB, voffB); PG8_STAGE(PG8_SA(0, 0), a2, voffA);
;             PG8_WAIT_V(8); PG8_WAIT_L(0); PG8_BAR; PG8_MMA(1, 0, At, B0); PG8_MMA(1, 1, At, B1); PG8_BAR; PG8_SCHED;
.LBB0_357:
	s_ashr_i32 s43, s42, 31
	s_lshl_b64 s[6:7], s[42:43], 19
	v_readlane_b32 s14, v253, 21
	v_readlane_b32 s15, v253, 22
	s_add_u32 s46, s14, s6
	s_addc_u32 s47, s15, s7
	s_and_b64 s[6:7], s[44:45], exec
	s_cselect_b32 s9, s47, s53
	s_cselect_b32 s13, s46, s52
	s_ashr_i32 s23, s22, 31
	s_lshl_b64 s[6:7], s[22:23], 19
	s_add_u32 s48, s28, s6
	s_addc_u32 s49, s35, s7
	s_and_b64 s[6:7], s[44:45], exec
	s_cselect_b32 s21, s49, s55
	s_cselect_b32 s23, s48, s54
	s_add_u32 s52, s52, 0x40080
	s_addc_u32 s53, s53, 0
	s_add_u32 s33, s54, 0x100
	s_addc_u32 s43, s55, 0
	s_mov_b32 s54, -2
	s_waitcnt lgkmcnt(0)
	s_cmp_eq_u64 s[18:19], 0
	s_cbranch_scc0 .Lprio_358
	s_setprio 1
.Lprio_358:
	s_add_u32 s0, s52, 0xfffc0080
	s_addc_u32 s6, s53, -1
	s_add_i32 s26, 0, 0x10000
	s_cmp_eq_u32 s54, 12
	s_cselect_b32 s15, s9, s6
	s_cselect_b32 s14, s13, s0
	s_cselect_b32 s7, s21, s43
	s_cselect_b32 s6, s23, s33
	s_add_i32 s0, 0, 0x14000
	v_add_u32_e32 v140, s26, v186
	v_add_u32_e32 v168, s0, v186
	ds_read_b128 v[128:131], v140
	ds_read_b128 v[132:135], v140 offset:1024
	ds_read_b128 v[136:139], v140 offset:2048
	ds_read_b128 v[140:143], v140 offset:3072
	ds_read_b128 v[144:147], v168
	ds_read_b128 v[148:151], v168 offset:1024
	ds_read_b128 v[152:155], v168 offset:2048
	ds_read_b128 v[168:171], v168 offset:3072
	v_lshl_add_u64 v[226:227], s[52:53], 0, v[164:165]
	s_add_i32 m0, s51, 0xc000
	ds_read_b128 v[172:175], v196
	ds_read_b128 v[198:201], v196 offset:1024
	ds_read_b128 v[202:205], v196 offset:2048
	ds_read_b128 v[206:209], v196 offset:3072
	ds_read_b128 v[210:213], v196 offset:4096
	ds_read_b128 v[214:217], v196 offset:5120
	ds_read_b128 v[218:221], v196 offset:6144
	ds_read_b128 v[222:225], v196 offset:7168
	global_load_lds_dwordx4 v[226:227], off
	v_lshl_add_u64 v[226:227], s[52:53], 0, v[166:167]
	s_add_i32 m0, s51, 0xe000
	s_nop 0
	global_load_lds_dwordx4 v[226:227], off
	s_waitcnt vmcnt(8)
	s_waitcnt lgkmcnt(0)
	s_barrier
	s_waitcnt lgkmcnt(0)
	v_mfma_f32_16x16x32_bf16 v[124:127], v[128:131], v[172:175], 0
	v_mfma_f32_16x16x32_bf16 v[120:123], v[136:139], v[172:175], 0
	v_mfma_f32_16x16x32_bf16 v[108:111], v[128:131], v[202:205], 0
	v_mfma_f32_16x16x32_bf16 v[104:107], v[136:139], v[202:205], 0
	v_mfma_f32_16x16x32_bf16 v[92:95], v[128:131], v[210:213], 0
	v_mfma_f32_16x16x32_bf16 v[88:91], v[136:139], v[210:213], 0
	v_mfma_f32_16x16x32_bf16 v[76:79], v[128:131], v[218:221], 0
	v_mfma_f32_16x16x32_bf16 v[72:75], v[136:139], v[218:221], 0
	v_mfma_f32_16x16x32_bf16 v[124:127], v[132:135], v[198:201], v[124:127]
	v_mfma_f32_16x16x32_bf16 v[120:123], v[140:143], v[198:201], v[120:123]
	v_mfma_f32_16x16x32_bf16 v[108:111], v[132:135], v[206:209], v[108:111]
	v_mfma_f32_16x16x32_bf16 v[104:107], v[140:143], v[206:209], v[104:107]
	v_mfma_f32_16x16x32_bf16 v[92:95], v[132:135], v[214:217], v[92:95]
	v_mfma_f32_16x16x32_bf16 v[88:91], v[140:143], v[214:217], v[88:91]
	v_mfma_f32_16x16x32_bf16 v[76:79], v[132:135], v[222:225], v[76:79]
	v_mfma_f32_16x16x32_bf16 v[72:75], v[140:143], v[222:225], v[72:75]
	v_mfma_f32_16x16x32_bf16 v[116:119], v[144:147], v[172:175], 0
	v_mfma_f32_16x16x32_bf16 v[112:115], v[152:155], v[172:175], 0
	v_mfma_f32_16x16x32_bf16 v[100:103], v[144:147], v[202:205], 0
	v_mfma_f32_16x16x32_bf16 v[96:99], v[152:155], v[202:205], 0
	v_mfma_f32_16x16x32_bf16 v[84:87], v[144:147], v[210:213], 0
	v_mfma_f32_16x16x32_bf16 v[80:83], v[152:155], v[210:213], 0
	v_mfma_f32_16x16x32_bf16 v[68:71], v[144:147], v[218:221], 0
	v_mfma_f32_16x16x32_bf16 v[64:67], v[152:155], v[218:221], 0
	v_mfma_f32_16x16x32_bf16 v[116:119], v[148:151], v[198:201], v[116:119]
	v_mfma_f32_16x16x32_bf16 v[112:115], v[168:171], v[198:201], v[112:115]
	v_mfma_f32_16x16x32_bf16 v[100:103], v[148:151], v[206:209], v[100:103]
	v_mfma_f32_16x16x32_bf16 v[96:99], v[168:171], v[206:209], v[96:99]
	v_mfma_f32_16x16x32_bf16 v[84:87], v[148:151], v[214:217], v[84:87]
	v_mfma_f32_16x16x32_bf16 v[80:83], v[168:171], v[214:217], v[80:83]
	v_mfma_f32_16x16x32_bf16 v[68:71], v[148:151], v[222:225], v[68:71]
	v_mfma_f32_16x16x32_bf16 v[64:67], v[168:171], v[222:225], v[64:67]
	s_barrier
	s_add_i32 s26, s26, s20
	v_lshl_add_u64 v[226:227], s[6:7], 0, v[160:161]
	s_mov_b32 m0, s26
	ds_read_b128 v[172:175], v196 offset:16384
	ds_read_b128 v[198:201], v196 offset:17408
	ds_read_b128 v[202:205], v196 offset:18432
	ds_read_b128 v[206:209], v196 offset:19456
	ds_read_b128 v[210:213], v196 offset:20480
	ds_read_b128 v[214:217], v196 offset:21504
	ds_read_b128 v[218:221], v196 offset:22528
	ds_read_b128 v[222:225], v196 offset:23552
	global_load_lds_dwordx4 v[226:227], off
	s_add_i32 m0, s26, 0x2000
	s_add_u32 s78, s6, 0x40000
	v_lshl_add_u64 v[228:229], s[6:7], 0, v[162:163]
	s_addc_u32 s79, s7, 0
	s_add_i32 s0, s0, s20
	global_load_lds_dwordx4 v[228:229], off
	v_lshl_add_u64 v[230:231], s[78:79], 0, v[160:161]
	s_mov_b32 m0, s0
	v_lshl_add_u64 v[232:233], s[14:15], 0, v[158:159]
	global_load_lds_dwordx4 v[230:231], off
	v_lshl_add_u64 v[230:231], s[78:79], 0, v[162:163]
	s_add_i32 m0, s0, 0x2000
	s_nop 0
	global_load_lds_dwordx4 v[230:231], off
	v_lshl_add_u64 v[230:231], s[14:15], 0, v[156:157]
	s_mov_b32 m0, s51
	s_nop 0
	global_load_lds_dwordx4 v[230:231], off
	s_mov_b32 m0, s56
	s_nop 0
	global_load_lds_dwordx4 v[232:233], off
	s_waitcnt vmcnt(8)
	s_waitcnt lgkmcnt(0)
	s_barrier
; #define PG8_STAGE(bufoff, gbase, voff) do { _Pragma("unroll") for (int _i = 0; _i < 2; ++_i) \
;         __builtin_amdgcn_global_load_lds((const unsigned*)((const char*)(gbase) + (voff)[_i]), (LAS unsigned*)(lds + (bufoff) + ldsw + _i * 8192), 16, 0, 0); } while (0)
; #define PG8_LDA(dst, b, h) do { _Pragma("unroll") for (int m = 0; m < 4; ++m) _Pragma("unroll") for (int k = 0; k < 2; ++k) dst[m][k] = *(const LAS bf16x8*)(lds + PG8_SA(b, h) + aoff + m * 2048 + k * 1024); } while (0)
; #define PG8_LDB(dst, b, h) do { _Pragma("unroll") for (int n = 0; n < 2; ++n) _Pragma("unroll") for (int k = 0; k < 2; ++k) dst[n][k] = *(const LAS bf16x8*)(lds + PG8_SB(b, h) + boff + n * 2048 + k * 1024); } while (0)
; #define PG8_MMA(ai, bj, At, Bt) do { __builtin_amdgcn_s_setprio(1); _Pragma("unroll") for (int m = 0; m < 4; ++m) _Pragma("unroll") for (int n = 0; n < 2; ++n) _Pragma("unroll") for (int k = 0; k < 2; ++k) \
;         acc[ai][bj][m][n] = __builtin_amdgcn_mfma_f32_16x16x32_bf16(Bt[n][k], At[m][k], acc[ai][bj][m][n], 0, 0, 0); __builtin_amdgcn_s_setprio(0); } while (0)
; #define PG8_WAIT_V(n) asm volatile("s_waitcnt vmcnt(" #n ")" ::: "memory")
; #define PG8_WAIT_L(n) asm volatile("s_waitcnt lgkmcnt(" #n ")" ::: "memory")
; #define PG8_BAR __builtin_amdgcn_s_barrier()
; #define PG8_SCHED __builtin_amdgcn_sched_barrier(0)
; template <class Epi, class Sched>
; __device__ __forceinline__ void gemm_phase(LAS unsigned char* lds, const Gemm g, const Sched& S, const Epi& E) {
;     ...
;             PG8_WAIT_V(8); PG8_WAIT_L(0); PG8_BAR; PG8_MMA(1, 0, At, B0); PG8_MMA(1, 1, At, B1); PG8_BAR; PG8_SCHED;
;             PG8_LDB(B0, 1, 0); PG8_LDB(B1, 1, 1); PG8_SCHED; PG8_LDA(At, 1, 0); PG8_STAGE(PG8_SA(0, 1), a2 + hstepA, voffA);
;             PG8_WAIT_V(8); PG8_WAIT_L(0); PG8_BAR; PG8_MMA(0, 0, At, B0); PG8_MMA(0, 1, At, B1); PG8_BAR; PG8_SCHED;
	s_waitcnt lgkmcnt(0)
	v_mfma_f32_16x16x32_bf16 v[60:63], v[128:131], v[172:175], 0
	v_mfma_f32_16x16x32_bf16 v[56:59], v[136:139], v[172:175], 0
	v_mfma_f32_16x16x32_bf16 v[44:47], v[128:131], v[202:205], 0
	v_mfma_f32_16x16x32_bf16 v[40:43], v[136:139], v[202:205], 0
	v_mfma_f32_16x16x32_bf16 v[28:31], v[128:131], v[210:213], 0
	v_mfma_f32_16x16x32_bf16 v[24:27], v[136:139], v[210:213], 0
	v_mfma_f32_16x16x32_bf16 v[12:15], v[128:131], v[218:221], 0
	v_mfma_f32_16x16x32_bf16 v[8:11], v[136:139], v[218:221], 0
	v_mfma_f32_16x16x32_bf16 v[60:63], v[132:135], v[198:201], v[60:63]
	v_mfma_f32_16x16x32_bf16 v[56:59], v[140:143], v[198:201], v[56:59]
	v_mfma_f32_16x16x32_bf16 v[44:47], v[132:135], v[206:209], v[44:47]
	v_mfma_f32_16x16x32_bf16 v[40:43], v[140:143], v[206:209], v[40:43]
	v_mfma_f32_16x16x32_bf16 v[28:31], v[132:135], v[214:217], v[28:31]
	v_mfma_f32_16x16x32_bf16 v[24:27], v[140:143], v[214:217], v[24:27]
	v_mfma_f32_16x16x32_bf16 v[12:15], v[132:135], v[222:225], v[12:15]
	v_mfma_f32_16x16x32_bf16 v[8:11], v[140:143], v[222:225], v[8:11]
	v_mfma_f32_16x16x32_bf16 v[52:55], v[144:147], v[172:175], 0
	v_mfma_f32_16x16x32_bf16 v[48:51], v[152:155], v[172:175], 0
	v_mfma_f32_16x16x32_bf16 v[36:39], v[144:147], v[202:205], 0
	v_mfma_f32_16x16x32_bf16 v[32:35], v[152:155], v[202:205], 0
	v_mfma_f32_16x16x32_bf16 v[20:23], v[144:147], v[210:213], 0
	v_mfma_f32_16x16x32_bf16 v[16:19], v[152:155], v[210:213], 0
	v_mfma_f32_16x16x32_bf16 v[4:7], v[144:147], v[218:221], 0
	v_mfma_f32_16x16x32_bf16 v[0:3], v[152:155], v[218:221], 0
	v_mfma_f32_16x16x32_bf16 v[52:55], v[148:151], v[198:201], v[52:55]
	v_mfma_f32_16x16x32_bf16 v[48:51], v[168:171], v[198:201], v[48:51]
	v_mfma_f32_16x16x32_bf16 v[36:39], v[148:151], v[206:209], v[36:39]
	v_mfma_f32_16x16x32_bf16 v[32:35], v[168:171], v[206:209], v[32:35]
	v_mfma_f32_16x16x32_bf16 v[20:23], v[148:151], v[214:217], v[20:23]
	v_mfma_f32_16x16x32_bf16 v[16:19], v[168:171], v[214:217], v[16:19]
	v_mfma_f32_16x16x32_bf16 v[4:7], v[148:151], v[222:225], v[4:7]
	v_mfma_f32_16x16x32_bf16 v[0:3], v[168:171], v[222:225], v[0:3]
	s_barrier
	s_add_i32 s0, 0, 0x18000
	s_add_i32 s26, 0, 0x1c000
	v_add_u32_e32 v140, s0, v186
	v_add_u32_e32 v168, s26, v186
	ds_read_b128 v[128:131], v140
	ds_read_b128 v[132:135], v140 offset:1024
	ds_read_b128 v[136:139], v140 offset:2048
	ds_read_b128 v[140:143], v140 offset:3072
	ds_read_b128 v[144:147], v168
	ds_read_b128 v[148:151], v168 offset:1024
	ds_read_b128 v[152:155], v168 offset:2048
	ds_read_b128 v[168:171], v168 offset:3072
	s_add_u32 s14, s14, 0x40000
	s_addc_u32 s15, s15, 0
	s_mov_b32 m0, s57
	v_lshl_add_u64 v[234:235], s[14:15], 0, v[156:157]
	ds_read_b128 v[172:175], v196 offset:32768
	ds_read_b128 v[198:201], v196 offset:33792
	ds_read_b128 v[202:205], v196 offset:34816
	ds_read_b128 v[206:209], v196 offset:35840
	ds_read_b128 v[210:213], v196 offset:36864
	ds_read_b128 v[214:217], v196 offset:37888
	ds_read_b128 v[218:221], v196 offset:38912
	ds_read_b128 v[222:225], v196 offset:39936
	global_load_lds_dwordx4 v[234:235], off
	v_lshl_add_u64 v[234:235], s[14:15], 0, v[158:159]
	s_mov_b32 m0, s68
	s_nop 0
	global_load_lds_dwordx4 v[234:235], off
	s_waitcnt vmcnt(8)
	s_waitcnt lgkmcnt(0)
	s_barrier
	s_waitcnt lgkmcnt(0)
	v_mfma_f32_16x16x32_bf16 v[124:127], v[128:131], v[172:175], v[124:127]
	v_mfma_f32_16x16x32_bf16 v[120:123], v[136:139], v[172:175], v[120:123]
	v_mfma_f32_16x16x32_bf16 v[108:111], v[128:131], v[202:205], v[108:111]
	v_mfma_f32_16x16x32_bf16 v[104:107], v[136:139], v[202:205], v[104:107]
	v_mfma_f32_16x16x32_bf16 v[92:95], v[128:131], v[210:213], v[92:95]
	v_mfma_f32_16x16x32_bf16 v[88:91], v[136:139], v[210:213], v[88:91]
	v_mfma_f32_16x16x32_bf16 v[76:79], v[128:131], v[218:221], v[76:79]
	v_mfma_f32_16x16x32_bf16 v[72:75], v[136:139], v[218:221], v[72:75]
	v_mfma_f32_16x16x32_bf16 v[124:127], v[132:135], v[198:201], v[124:127]
	v_mfma_f32_16x16x32_bf16 v[120:123], v[140:143], v[198:201], v[120:123]
	v_mfma_f32_16x16x32_bf16 v[108:111], v[132:135], v[206:209], v[108:111]
	v_mfma_f32_16x16x32_bf16 v[104:107], v[140:143], v[206:209], v[104:107]
	v_mfma_f32_16x16x32_bf16 v[92:95], v[132:135], v[214:217], v[92:95]
	v_mfma_f32_16x16x32_bf16 v[88:91], v[140:143], v[214:217], v[88:91]
	v_mfma_f32_16x16x32_bf16 v[76:79], v[132:135], v[222:225], v[76:79]
	v_mfma_f32_16x16x32_bf16 v[72:75], v[140:143], v[222:225], v[72:75]
	v_mfma_f32_16x16x32_bf16 v[116:119], v[144:147], v[172:175], v[116:119]
	v_mfma_f32_16x16x32_bf16 v[112:115], v[152:155], v[172:175], v[112:115]
	v_mfma_f32_16x16x32_bf16 v[100:103], v[144:147], v[202:205], v[100:103]
	v_mfma_f32_16x16x32_bf16 v[96:99], v[152:155], v[202:205], v[96:99]
	v_mfma_f32_16x16x32_bf16 v[84:87], v[144:147], v[210:213], v[84:87]
	v_mfma_f32_16x16x32_bf16 v[80:83], v[152:155], v[210:213], v[80:83]
	v_mfma_f32_16x16x32_bf16 v[68:71], v[144:147], v[218:221], v[68:71]
	v_mfma_f32_16x16x32_bf16 v[64:67], v[152:155], v[218:221], v[64:67]
	v_mfma_f32_16x16x32_bf16 v[116:119], v[148:151], v[198:201], v[116:119]
	v_mfma_f32_16x16x32_bf16 v[112:115], v[168:171], v[198:201], v[112:115]
	v_mfma_f32_16x16x32_bf16 v[100:103], v[148:151], v[206:209], v[100:103]
	v_mfma_f32_16x16x32_bf16 v[96:99], v[168:171], v[206:209], v[96:99]
	v_mfma_f32_16x16x32_bf16 v[84:87], v[148:151], v[214:217], v[84:87]
	v_mfma_f32_16x16x32_bf16 v[80:83], v[168:171], v[214:217], v[80:83]
	v_mfma_f32_16x16x32_bf16 v[68:71], v[148:151], v[222:225], v[68:71]
	v_mfma_f32_16x16x32_bf16 v[64:67], v[168:171], v[222:225], v[64:67]
	s_barrier
; #define PG8_STAGE(bufoff, gbase, voff) do { _Pragma("unroll") for (int _i = 0; _i < 2; ++_i) \
;         __builtin_amdgcn_global_load_lds((const unsigned*)((const char*)(gbase) + (voff)[_i]), (LAS unsigned*)(lds + (bufoff) + ldsw + _i * 8192), 16, 0, 0); } while (0)
; #define PG8_LDA(dst, b, h) do { _Pragma("unroll") for (int m = 0; m < 4; ++m) _Pragma("unroll") for (int k = 0; k < 2; ++k) dst[m][k] = *(const LAS bf16x8*)(lds + PG8_SA(b, h) + aoff + m * 2048 + k * 1024); } while (0)
; #define PG8_LDB(dst, b, h) do { _Pragma("unroll") for (int n = 0; n < 2; ++n) _Pragma("unroll") for (int k = 0; k < 2; ++k) dst[n][k] = *(const LAS bf16x8*)(lds + PG8_SB(b, h) + boff + n * 2048 + k * 1024); } while (0)
; #define PG8_MMA(ai, bj, At, Bt) do { __builtin_amdgcn_s_setprio(1); _Pragma("unroll") for (int m = 0; m < 4; ++m) _Pragma("unroll") for (int n = 0; n < 2; ++n) _Pragma("unroll") for (int k = 0; k < 2; ++k) \
;         acc[ai][bj][m][n] = __builtin_amdgcn_mfma_f32_16x16x32_bf16(Bt[n][k], At[m][k], acc[ai][bj][m][n], 0, 0, 0); __builtin_amdgcn_s_setprio(0); } while (0)
; #define PG8_WAIT_V(n) asm volatile("s_waitcnt vmcnt(" #n ")" ::: "memory")
; #define PG8_WAIT_L(n) asm volatile("s_waitcnt lgkmcnt(" #n ")" ::: "memory")
; #define PG8_BAR __builtin_amdgcn_s_barrier()
; #define PG8_SCHED __builtin_amdgcn_sched_barrier(0)
; template <class Epi, class Sched>
; __device__ __forceinline__ void gemm_phase(LAS unsigned char* lds, const Gemm g, const Sched& S, const Epi& E) {
;     ...
;             PG8_LDB(B0, 0, 0); PG8_LDB(B1, 0, 1); PG8_SCHED; PG8_LDA(At, 0, 0); PG8_STAGE(PG8_SA(1, 1), a1 + hstepA, voffA);
;             PG8_WAIT_V(8); PG8_WAIT_L(0); PG8_BAR; PG8_MMA(0, 0, At, B0); PG8_MMA(0, 1, At, B1); PG8_BAR; PG8_SCHED;
;     ...
;             PG8_LDA(At, 1, 1); PG8_STAGE(PG8_SB(1, 0), b3, voffB); PG8_STAGE(PG8_SB(1, 1), b3 + hstepB, voffB); PG8_STAGE(PG8_SA(1, 0), a3, voffA);
;             PG8_WAIT_V(8); PG8_WAIT_L(0); PG8_BAR; PG8_MMA(1, 0, At, B0); PG8_MMA(1, 1, At, B1); PG8_BAR; PG8_SCHED;
	s_add_i32 s0, s0, s20
	v_lshl_add_u64 v[226:227], v[226:227], 0, s[30:31]
	s_mov_b32 m0, s0
	ds_read_b128 v[172:175], v196 offset:49152
	ds_read_b128 v[198:201], v196 offset:50176
	ds_read_b128 v[202:205], v196 offset:51200
	ds_read_b128 v[206:209], v196 offset:52224
	ds_read_b128 v[210:213], v196 offset:53248
	ds_read_b128 v[214:217], v196 offset:54272
	ds_read_b128 v[218:221], v196 offset:55296
	ds_read_b128 v[222:225], v196 offset:56320
	global_load_lds_dwordx4 v[226:227], off
	s_add_i32 m0, s0, 0x2000
	s_add_u32 s6, s6, 0x40080
	v_lshl_add_u64 v[226:227], v[228:229], 0, s[30:31]
	s_addc_u32 s7, s7, 0
	s_add_i32 s0, s26, s20
	global_load_lds_dwordx4 v[226:227], off
	v_lshl_add_u64 v[226:227], s[6:7], 0, v[160:161]
	s_mov_b32 m0, s0
	s_nop 0
	global_load_lds_dwordx4 v[226:227], off
	v_lshl_add_u64 v[226:227], s[6:7], 0, v[162:163]
	s_add_i32 m0, s0, 0x2000
	s_nop 0
	global_load_lds_dwordx4 v[226:227], off
	v_lshl_add_u64 v[226:227], v[230:231], 0, s[30:31]
	s_mov_b32 m0, s24
	s_nop 0
	global_load_lds_dwordx4 v[226:227], off
	v_lshl_add_u64 v[226:227], v[232:233], 0, s[30:31]
	s_mov_b32 m0, s25
	s_nop 0
	global_load_lds_dwordx4 v[226:227], off
	s_waitcnt vmcnt(8)
	s_waitcnt lgkmcnt(0)
	s_barrier
	s_waitcnt lgkmcnt(0)
	v_mfma_f32_16x16x32_bf16 v[60:63], v[128:131], v[172:175], v[60:63]
	v_mfma_f32_16x16x32_bf16 v[56:59], v[136:139], v[172:175], v[56:59]
	v_mfma_f32_16x16x32_bf16 v[44:47], v[128:131], v[202:205], v[44:47]
	v_mfma_f32_16x16x32_bf16 v[40:43], v[136:139], v[202:205], v[40:43]
	v_mfma_f32_16x16x32_bf16 v[28:31], v[128:131], v[210:213], v[28:31]
	v_mfma_f32_16x16x32_bf16 v[24:27], v[136:139], v[210:213], v[24:27]
	v_mfma_f32_16x16x32_bf16 v[12:15], v[128:131], v[218:221], v[12:15]
	v_mfma_f32_16x16x32_bf16 v[8:11], v[136:139], v[218:221], v[8:11]
	v_mfma_f32_16x16x32_bf16 v[60:63], v[132:135], v[198:201], v[60:63]
	v_mfma_f32_16x16x32_bf16 v[56:59], v[140:143], v[198:201], v[56:59]
	v_mfma_f32_16x16x32_bf16 v[44:47], v[132:135], v[206:209], v[44:47]
	v_mfma_f32_16x16x32_bf16 v[40:43], v[140:143], v[206:209], v[40:43]
	v_mfma_f32_16x16x32_bf16 v[28:31], v[132:135], v[214:217], v[28:31]
	v_mfma_f32_16x16x32_bf16 v[24:27], v[140:143], v[214:217], v[24:27]
	v_mfma_f32_16x16x32_bf16 v[12:15], v[132:135], v[222:225], v[12:15]
	v_mfma_f32_16x16x32_bf16 v[8:11], v[140:143], v[222:225], v[8:11]
	v_mfma_f32_16x16x32_bf16 v[52:55], v[144:147], v[172:175], v[52:55]
	v_mfma_f32_16x16x32_bf16 v[48:51], v[152:155], v[172:175], v[48:51]
	v_mfma_f32_16x16x32_bf16 v[36:39], v[144:147], v[202:205], v[36:39]
	v_mfma_f32_16x16x32_bf16 v[32:35], v[152:155], v[202:205], v[32:35]
	v_mfma_f32_16x16x32_bf16 v[20:23], v[144:147], v[210:213], v[20:23]
	v_mfma_f32_16x16x32_bf16 v[16:19], v[152:155], v[210:213], v[16:19]
	v_mfma_f32_16x16x32_bf16 v[4:7], v[144:147], v[218:221], v[4:7]
	v_mfma_f32_16x16x32_bf16 v[0:3], v[152:155], v[218:221], v[0:3]
	v_mfma_f32_16x16x32_bf16 v[52:55], v[148:151], v[198:201], v[52:55]
	v_mfma_f32_16x16x32_bf16 v[48:51], v[168:171], v[198:201], v[48:51]
	v_mfma_f32_16x16x32_bf16 v[36:39], v[148:151], v[206:209], v[36:39]
	v_mfma_f32_16x16x32_bf16 v[32:35], v[168:171], v[206:209], v[32:35]
	v_mfma_f32_16x16x32_bf16 v[20:23], v[148:151], v[214:217], v[20:23]
	v_mfma_f32_16x16x32_bf16 v[16:19], v[168:171], v[214:217], v[16:19]
	v_mfma_f32_16x16x32_bf16 v[4:7], v[148:151], v[222:225], v[4:7]
	v_mfma_f32_16x16x32_bf16 v[0:3], v[168:171], v[222:225], v[0:3]
	s_barrier
	s_add_i32 s54, s54, 2
	s_add_u32 s52, s52, 0x100
	s_addc_u32 s53, s53, 0
	s_add_u32 s33, s33, 0x100
	s_addc_u32 s43, s43, 0
	s_cmp_gt_u32 s54, 13
.LBB0_358:
	s_add_u32 s0, s52, 0xfffc0080
	s_addc_u32 s6, s53, -1
	s_add_i32 s26, 0, 0x10000
	s_cmp_eq_u32 s54, 12
	s_cselect_b32 s15, s9, s6
	s_cselect_b32 s14, s13, s0
	s_cselect_b32 s7, s21, s43
	s_cselect_b32 s6, s23, s33
	s_add_i32 s0, 0, 0x14000
	v_add_u32_e32 v140, s26, v186
	v_add_u32_e32 v168, s0, v186
	ds_read_b128 v[128:131], v140
	ds_read_b128 v[132:135], v140 offset:1024
	ds_read_b128 v[136:139], v140 offset:2048
	ds_read_b128 v[140:143], v140 offset:3072
	ds_read_b128 v[144:147], v168
	ds_read_b128 v[148:151], v168 offset:1024
	ds_read_b128 v[152:155], v168 offset:2048
	ds_read_b128 v[168:171], v168 offset:3072
	v_lshl_add_u64 v[226:227], s[52:53], 0, v[164:165]
	s_add_i32 m0, s51, 0xc000
	ds_read_b128 v[172:175], v196
	ds_read_b128 v[198:201], v196 offset:1024
	ds_read_b128 v[202:205], v196 offset:2048
	ds_read_b128 v[206:209], v196 offset:3072
	ds_read_b128 v[210:213], v196 offset:4096
	ds_read_b128 v[214:217], v196 offset:5120
	ds_read_b128 v[218:221], v196 offset:6144
	ds_read_b128 v[222:225], v196 offset:7168
	global_load_lds_dwordx4 v[226:227], off
	v_lshl_add_u64 v[226:227], s[52:53], 0, v[166:167]
	s_add_i32 m0, s51, 0xe000
	s_nop 0
	global_load_lds_dwordx4 v[226:227], off
	s_waitcnt vmcnt(8)
	s_waitcnt lgkmcnt(0)
	s_barrier
; #define PG8_STAGE(bufoff, gbase, voff) do { _Pragma("unroll") for (int _i = 0; _i < 2; ++_i) \
;         __builtin_amdgcn_global_load_lds((const unsigned*)((const char*)(gbase) + (voff)[_i]), (LAS unsigned*)(lds + (bufoff) + ldsw + _i * 8192), 16, 0, 0); } while (0)
; #define PG8_LDA(dst, b, h) do { _Pragma("unroll") for (int m = 0; m < 4; ++m) _Pragma("unroll") for (int k = 0; k < 2; ++k) dst[m][k] = *(const LAS bf16x8*)(lds + PG8_SA(b, h) + aoff + m * 2048 + k * 1024); } while (0)
; #define PG8_LDB(dst, b, h) do { _Pragma("unroll") for (int n = 0; n < 2; ++n) _Pragma("unroll") for (int k = 0; k < 2; ++k) dst[n][k] = *(const LAS bf16x8*)(lds + PG8_SB(b, h) + boff + n * 2048 + k * 1024); } while (0)
; #define PG8_MMA(ai, bj, At, Bt) do { __builtin_amdgcn_s_setprio(1); _Pragma("unroll") for (int m = 0; m < 4; ++m) _Pragma("unroll") for (int n = 0; n < 2; ++n) _Pragma("unroll") for (int k = 0; k < 2; ++k) \
;         acc[ai][bj][m][n] = __builtin_amdgcn_mfma_f32_16x16x32_bf16(Bt[n][k], At[m][k], acc[ai][bj][m][n], 0, 0, 0); __builtin_amdgcn_s_setprio(0); } while (0)
; #define PG8_WAIT_V(n) asm volatile("s_waitcnt vmcnt(" #n ")" ::: "memory")
; #define PG8_WAIT_L(n) asm volatile("s_waitcnt lgkmcnt(" #n ")" ::: "memory")
; #define PG8_BAR __builtin_amdgcn_s_barrier()
; #define PG8_SCHED __builtin_amdgcn_sched_barrier(0)
; template <class Epi, class Sched>
; __device__ __forceinline__ void gemm_phase(LAS unsigned char* lds, const Gemm g, const Sched& S, const Epi& E) {
;     ...
;             PG8_WAIT_V(8); PG8_WAIT_L(0); PG8_BAR; PG8_MMA(0, 0, At, B0); PG8_MMA(0, 1, At, B1); PG8_BAR; PG8_SCHED;
;             PG8_LDA(At, 0, 1); PG8_STAGE(PG8_SB(0, 0), b2, voffB); PG8_STAGE(PG8_SB(0, 1), b2 + hstepB, voffB); PG8_STAGE(PG8_SA(0, 0), a2, voffA);
;             PG8_WAIT_V(8); PG8_WAIT_L(0); PG8_BAR; PG8_MMA(1, 0, At, B0); PG8_MMA(1, 1, At, B1); PG8_BAR; PG8_SCHED;
;             PG8_LDB(B0, 1, 0); PG8_LDB(B1, 1, 1); PG8_SCHED; PG8_LDA(At, 1, 0); PG8_STAGE(PG8_SA(0, 1), a2 + hstepA, voffA);
;             PG8_WAIT_V(8); PG8_WAIT_L(0); PG8_BAR; PG8_MMA(0, 0, At, B0); PG8_MMA(0, 1, At, B1); PG8_BAR; PG8_SCHED;
	s_waitcnt lgkmcnt(0)
	v_mfma_f32_16x16x32_bf16 v[124:127], v[128:131], v[172:175], v[124:127]
	v_mfma_f32_16x16x32_bf16 v[120:123], v[136:139], v[172:175], v[120:123]
	v_mfma_f32_16x16x32_bf16 v[108:111], v[128:131], v[202:205], v[108:111]
	v_mfma_f32_16x16x32_bf16 v[104:107], v[136:139], v[202:205], v[104:107]
	v_mfma_f32_16x16x32_bf16 v[92:95], v[128:131], v[210:213], v[92:95]
	v_mfma_f32_16x16x32_bf16 v[88:91], v[136:139], v[210:213], v[88:91]
	v_mfma_f32_16x16x32_bf16 v[76:79], v[128:131], v[218:221], v[76:79]
	v_mfma_f32_16x16x32_bf16 v[72:75], v[136:139], v[218:221], v[72:75]
	v_mfma_f32_16x16x32_bf16 v[124:127], v[132:135], v[198:201], v[124:127]
	v_mfma_f32_16x16x32_bf16 v[120:123], v[140:143], v[198:201], v[120:123]
	v_mfma_f32_16x16x32_bf16 v[108:111], v[132:135], v[206:209], v[108:111]
	v_mfma_f32_16x16x32_bf16 v[104:107], v[140:143], v[206:209], v[104:107]
	v_mfma_f32_16x16x32_bf16 v[92:95], v[132:135], v[214:217], v[92:95]
	v_mfma_f32_16x16x32_bf16 v[88:91], v[140:143], v[214:217], v[88:91]
	v_mfma_f32_16x16x32_bf16 v[76:79], v[132:135], v[222:225], v[76:79]
	v_mfma_f32_16x16x32_bf16 v[72:75], v[140:143], v[222:225], v[72:75]
	v_mfma_f32_16x16x32_bf16 v[116:119], v[144:147], v[172:175], v[116:119]
	v_mfma_f32_16x16x32_bf16 v[112:115], v[152:155], v[172:175], v[112:115]
	v_mfma_f32_16x16x32_bf16 v[100:103], v[144:147], v[202:205], v[100:103]
	v_mfma_f32_16x16x32_bf16 v[96:99], v[152:155], v[202:205], v[96:99]
	v_mfma_f32_16x16x32_bf16 v[84:87], v[144:147], v[210:213], v[84:87]
	v_mfma_f32_16x16x32_bf16 v[80:83], v[152:155], v[210:213], v[80:83]
	v_mfma_f32_16x16x32_bf16 v[68:71], v[144:147], v[218:221], v[68:71]
	v_mfma_f32_16x16x32_bf16 v[64:67], v[152:155], v[218:221], v[64:67]
	v_mfma_f32_16x16x32_bf16 v[116:119], v[148:151], v[198:201], v[116:119]
	v_mfma_f32_16x16x32_bf16 v[112:115], v[168:171], v[198:201], v[112:115]
	v_mfma_f32_16x16x32_bf16 v[100:103], v[148:151], v[206:209], v[100:103]
	v_mfma_f32_16x16x32_bf16 v[96:99], v[168:171], v[206:209], v[96:99]
	v_mfma_f32_16x16x32_bf16 v[84:87], v[148:151], v[214:217], v[84:87]
	v_mfma_f32_16x16x32_bf16 v[80:83], v[168:171], v[214:217], v[80:83]
	v_mfma_f32_16x16x32_bf16 v[68:71], v[148:151], v[222:225], v[68:71]
	v_mfma_f32_16x16x32_bf16 v[64:67], v[168:171], v[222:225], v[64:67]
	s_barrier
	s_add_i32 s26, s26, s20
	v_lshl_add_u64 v[226:227], s[6:7], 0, v[160:161]
	s_mov_b32 m0, s26
	ds_read_b128 v[172:175], v196 offset:16384
	ds_read_b128 v[198:201], v196 offset:17408
	ds_read_b128 v[202:205], v196 offset:18432
	ds_read_b128 v[206:209], v196 offset:19456
	ds_read_b128 v[210:213], v196 offset:20480
	ds_read_b128 v[214:217], v196 offset:21504
	ds_read_b128 v[218:221], v196 offset:22528
	ds_read_b128 v[222:225], v196 offset:23552
	global_load_lds_dwordx4 v[226:227], off
	s_add_i32 m0, s26, 0x2000
	s_add_u32 s78, s6, 0x40000
	v_lshl_add_u64 v[228:229], s[6:7], 0, v[162:163]
	s_addc_u32 s79, s7, 0
	s_add_i32 s0, s0, s20
	global_load_lds_dwordx4 v[228:229], off
	v_lshl_add_u64 v[230:231], s[78:79], 0, v[160:161]
	s_mov_b32 m0, s0
	v_lshl_add_u64 v[232:233], s[14:15], 0, v[158:159]
	global_load_lds_dwordx4 v[230:231], off
	v_lshl_add_u64 v[230:231], s[78:79], 0, v[162:163]
	s_add_i32 m0, s0, 0x2000
	s_nop 0
	global_load_lds_dwordx4 v[230:231], off
	v_lshl_add_u64 v[230:231], s[14:15], 0, v[156:157]
	s_mov_b32 m0, s51
	s_nop 0
	global_load_lds_dwordx4 v[230:231], off
	s_mov_b32 m0, s56
	s_nop 0
	global_load_lds_dwordx4 v[232:233], off
	s_waitcnt vmcnt(8)
	s_waitcnt lgkmcnt(0)
	s_barrier
	s_waitcnt lgkmcnt(0)
	v_mfma_f32_16x16x32_bf16 v[60:63], v[128:131], v[172:175], v[60:63]
	v_mfma_f32_16x16x32_bf16 v[56:59], v[136:139], v[172:175], v[56:59]
	v_mfma_f32_16x16x32_bf16 v[44:47], v[128:131], v[202:205], v[44:47]
	v_mfma_f32_16x16x32_bf16 v[40:43], v[136:139], v[202:205], v[40:43]
	v_mfma_f32_16x16x32_bf16 v[28:31], v[128:131], v[210:213], v[28:31]
	v_mfma_f32_16x16x32_bf16 v[24:27], v[136:139], v[210:213], v[24:27]
	v_mfma_f32_16x16x32_bf16 v[12:15], v[128:131], v[218:221], v[12:15]
	v_mfma_f32_16x16x32_bf16 v[8:11], v[136:139], v[218:221], v[8:11]
	v_mfma_f32_16x16x32_bf16 v[60:63], v[132:135], v[198:201], v[60:63]
	v_mfma_f32_16x16x32_bf16 v[56:59], v[140:143], v[198:201], v[56:59]
	v_mfma_f32_16x16x32_bf16 v[44:47], v[132:135], v[206:209], v[44:47]
	v_mfma_f32_16x16x32_bf16 v[40:43], v[140:143], v[206:209], v[40:43]
	v_mfma_f32_16x16x32_bf16 v[28:31], v[132:135], v[214:217], v[28:31]
	v_mfma_f32_16x16x32_bf16 v[24:27], v[140:143], v[214:217], v[24:27]
	v_mfma_f32_16x16x32_bf16 v[12:15], v[132:135], v[222:225], v[12:15]
	v_mfma_f32_16x16x32_bf16 v[8:11], v[140:143], v[222:225], v[8:11]
	v_mfma_f32_16x16x32_bf16 v[52:55], v[144:147], v[172:175], v[52:55]
	v_mfma_f32_16x16x32_bf16 v[48:51], v[152:155], v[172:175], v[48:51]
	v_mfma_f32_16x16x32_bf16 v[36:39], v[144:147], v[202:205], v[36:39]
	v_mfma_f32_16x16x32_bf16 v[32:35], v[152:155], v[202:205], v[32:35]
	v_mfma_f32_16x16x32_bf16 v[20:23], v[144:147], v[210:213], v[20:23]
	v_mfma_f32_16x16x32_bf16 v[16:19], v[152:155], v[210:213], v[16:19]
	v_mfma_f32_16x16x32_bf16 v[4:7], v[144:147], v[218:221], v[4:7]
	v_mfma_f32_16x16x32_bf16 v[0:3], v[152:155], v[218:221], v[0:3]
	v_mfma_f32_16x16x32_bf16 v[52:55], v[148:151], v[198:201], v[52:55]
	v_mfma_f32_16x16x32_bf16 v[48:51], v[168:171], v[198:201], v[48:51]
	v_mfma_f32_16x16x32_bf16 v[36:39], v[148:151], v[206:209], v[36:39]
	v_mfma_f32_16x16x32_bf16 v[32:35], v[168:171], v[206:209], v[32:35]
	v_mfma_f32_16x16x32_bf16 v[20:23], v[148:151], v[214:217], v[20:23]
	v_mfma_f32_16x16x32_bf16 v[16:19], v[168:171], v[214:217], v[16:19]
	v_mfma_f32_16x16x32_bf16 v[4:7], v[148:151], v[222:225], v[4:7]
	v_mfma_f32_16x16x32_bf16 v[0:3], v[168:171], v[222:225], v[0:3]
	s_barrier
; #define PG8_STAGE(bufoff, gbase, voff) do { _Pragma("unroll") for (int _i = 0; _i < 2; ++_i) \
;         __builtin_amdgcn_global_load_lds((const unsigned*)((const char*)(gbase) + (voff)[_i]), (LAS unsigned*)(lds + (bufoff) + ldsw + _i * 8192), 16, 0, 0); } while (0)
; #define PG8_LDA(dst, b, h) do { _Pragma("unroll") for (int m = 0; m < 4; ++m) _Pragma("unroll") for (int k = 0; k < 2; ++k) dst[m][k] = *(const LAS bf16x8*)(lds + PG8_SA(b, h) + aoff + m * 2048 + k * 1024); } while (0)
; #define PG8_LDB(dst, b, h) do { _Pragma("unroll") for (int n = 0; n < 2; ++n) _Pragma("unroll") for (int k = 0; k < 2; ++k) dst[n][k] = *(const LAS bf16x8*)(lds + PG8_SB(b, h) + boff + n * 2048 + k * 1024); } while (0)
; #define PG8_MMA(ai, bj, At, Bt) do { __builtin_amdgcn_s_setprio(1); _Pragma("unroll") for (int m = 0; m < 4; ++m) _Pragma("unroll") for (int n = 0; n < 2; ++n) _Pragma("unroll") for (int k = 0; k < 2; ++k) \
;         acc[ai][bj][m][n] = __builtin_amdgcn_mfma_f32_16x16x32_bf16(Bt[n][k], At[m][k], acc[ai][bj][m][n], 0, 0, 0); __builtin_amdgcn_s_setprio(0); } while (0)
; #define PG8_WAIT_V(n) asm volatile("s_waitcnt vmcnt(" #n ")" ::: "memory")
; #define PG8_WAIT_L(n) asm volatile("s_waitcnt lgkmcnt(" #n ")" ::: "memory")
; #define PG8_BAR __builtin_amdgcn_s_barrier()
; #define PG8_SCHED __builtin_amdgcn_sched_barrier(0)
; template <class Epi, class Sched>
; __device__ __forceinline__ void gemm_phase(LAS unsigned char* lds, const Gemm g, const Sched& S, const Epi& E) {
;     ...
;             PG8_LDB(B0, 1, 0); PG8_LDB(B1, 1, 1); PG8_SCHED; PG8_LDA(At, 1, 0); PG8_STAGE(PG8_SA(0, 1), a2 + hstepA, voffA);
;             PG8_WAIT_V(8); PG8_WAIT_L(0); PG8_BAR; PG8_MMA(0, 0, At, B0); PG8_MMA(0, 1, At, B1); PG8_BAR; PG8_SCHED;
	s_add_i32 s0, 0, 0x18000
	s_add_i32 s26, 0, 0x1c000
	v_add_u32_e32 v140, s0, v186
	v_add_u32_e32 v168, s26, v186
	ds_read_b128 v[128:131], v140
	ds_read_b128 v[132:135], v140 offset:1024
	ds_read_b128 v[136:139], v140 offset:2048
	ds_read_b128 v[140:143], v140 offset:3072
	ds_read_b128 v[144:147], v168
	ds_read_b128 v[148:151], v168 offset:1024
	ds_read_b128 v[152:155], v168 offset:2048
	ds_read_b128 v[168:171], v168 offset:3072
	s_add_u32 s14, s14, 0x40000
	s_addc_u32 s15, s15, 0
	s_mov_b32 m0, s57
	v_lshl_add_u64 v[234:235], s[14:15], 0, v[156:157]
	ds_read_b128 v[172:175], v196 offset:32768
	ds_read_b128 v[198:201], v196 offset:33792
	ds_read_b128 v[202:205], v196 offset:34816
	ds_read_b128 v[206:209], v196 offset:35840
	ds_read_b128 v[210:213], v196 offset:36864
	ds_read_b128 v[214:217], v196 offset:37888
	ds_read_b128 v[218:221], v196 offset:38912
	ds_read_b128 v[222:225], v196 offset:39936
	global_load_lds_dwordx4 v[234:235], off
	v_lshl_add_u64 v[234:235], s[14:15], 0, v[158:159]
	s_mov_b32 m0, s68
	s_nop 0
	global_load_lds_dwordx4 v[234:235], off
	s_waitcnt vmcnt(8)
	s_waitcnt lgkmcnt(0)
	s_barrier
	s_waitcnt lgkmcnt(0)
	v_mfma_f32_16x16x32_bf16 v[124:127], v[128:131], v[172:175], v[124:127]
	v_mfma_f32_16x16x32_bf16 v[120:123], v[136:139], v[172:175], v[120:123]
	v_mfma_f32_16x16x32_bf16 v[108:111], v[128:131], v[202:205], v[108:111]
	v_mfma_f32_16x16x32_bf16 v[104:107], v[136:139], v[202:205], v[104:107]
	v_mfma_f32_16x16x32_bf16 v[92:95], v[128:131], v[210:213], v[92:95]
	v_mfma_f32_16x16x32_bf16 v[88:91], v[136:139], v[210:213], v[88:91]
	v_mfma_f32_16x16x32_bf16 v[76:79], v[128:131], v[218:221], v[76:79]
	v_mfma_f32_16x16x32_bf16 v[72:75], v[136:139], v[218:221], v[72:75]
	v_mfma_f32_16x16x32_bf16 v[124:127], v[132:135], v[198:201], v[124:127]
	v_mfma_f32_16x16x32_bf16 v[120:123], v[140:143], v[198:201], v[120:123]
	v_mfma_f32_16x16x32_bf16 v[108:111], v[132:135], v[206:209], v[108:111]
	v_mfma_f32_16x16x32_bf16 v[104:107], v[140:143], v[206:209], v[104:107]
	v_mfma_f32_16x16x32_bf16 v[92:95], v[132:135], v[214:217], v[92:95]
	v_mfma_f32_16x16x32_bf16 v[88:91], v[140:143], v[214:217], v[88:91]
	v_mfma_f32_16x16x32_bf16 v[76:79], v[132:135], v[222:225], v[76:79]
	v_mfma_f32_16x16x32_bf16 v[72:75], v[140:143], v[222:225], v[72:75]
	v_mfma_f32_16x16x32_bf16 v[116:119], v[144:147], v[172:175], v[116:119]
	v_mfma_f32_16x16x32_bf16 v[112:115], v[152:155], v[172:175], v[112:115]
	v_mfma_f32_16x16x32_bf16 v[100:103], v[144:147], v[202:205], v[100:103]
	v_mfma_f32_16x16x32_bf16 v[96:99], v[152:155], v[202:205], v[96:99]
	v_mfma_f32_16x16x32_bf16 v[84:87], v[144:147], v[210:213], v[84:87]
	v_mfma_f32_16x16x32_bf16 v[80:83], v[152:155], v[210:213], v[80:83]
	v_mfma_f32_16x16x32_bf16 v[68:71], v[144:147], v[218:221], v[68:71]
	v_mfma_f32_16x16x32_bf16 v[64:67], v[152:155], v[218:221], v[64:67]
	v_mfma_f32_16x16x32_bf16 v[116:119], v[148:151], v[198:201], v[116:119]
	v_mfma_f32_16x16x32_bf16 v[112:115], v[168:171], v[198:201], v[112:115]
	v_mfma_f32_16x16x32_bf16 v[100:103], v[148:151], v[206:209], v[100:103]
	v_mfma_f32_16x16x32_bf16 v[96:99], v[168:171], v[206:209], v[96:99]
	v_mfma_f32_16x16x32_bf16 v[84:87], v[148:151], v[214:217], v[84:87]
	v_mfma_f32_16x16x32_bf16 v[80:83], v[168:171], v[214:217], v[80:83]
	v_mfma_f32_16x16x32_bf16 v[68:71], v[148:151], v[222:225], v[68:71]
	v_mfma_f32_16x16x32_bf16 v[64:67], v[168:171], v[222:225], v[64:67]
	s_barrier
; #define PG8_STAGE(bufoff, gbase, voff) do { _Pragma("unroll") for (int _i = 0; _i < 2; ++_i) \
;         __builtin_amdgcn_global_load_lds((const unsigned*)((const char*)(gbase) + (voff)[_i]), (LAS unsigned*)(lds + (bufoff) + ldsw + _i * 8192), 16, 0, 0); } while (0)
; #define PG8_LDA(dst, b, h) do { _Pragma("unroll") for (int m = 0; m < 4; ++m) _Pragma("unroll") for (int k = 0; k < 2; ++k) dst[m][k] = *(const LAS bf16x8*)(lds + PG8_SA(b, h) + aoff + m * 2048 + k * 1024); } while (0)
; #define PG8_MMA(ai, bj, At, Bt) do { __builtin_amdgcn_s_setprio(1); _Pragma("unroll") for (int m = 0; m < 4; ++m) _Pragma("unroll") for (int n = 0; n < 2; ++n) _Pragma("unroll") for (int k = 0; k < 2; ++k) \
;         acc[ai][bj][m][n] = __builtin_amdgcn_mfma_f32_16x16x32_bf16(Bt[n][k], At[m][k], acc[ai][bj][m][n], 0, 0, 0); __builtin_amdgcn_s_setprio(0); } while (0)
; #define PG8_WAIT_V(n) asm volatile("s_waitcnt vmcnt(" #n ")" ::: "memory")
; #define PG8_WAIT_L(n) asm volatile("s_waitcnt lgkmcnt(" #n ")" ::: "memory")
; #define PG8_BAR __builtin_amdgcn_s_barrier()
; #define PG8_SCHED __builtin_amdgcn_sched_barrier(0)
; template <class Epi, class Sched>
; __device__ __forceinline__ void gemm_phase(LAS unsigned char* lds, const Gemm g, const Sched& S, const Epi& E) {
;     ...
;             PG8_LDA(At, 1, 1); PG8_STAGE(PG8_SB(1, 0), b3, voffB); PG8_STAGE(PG8_SB(1, 1), b3 + hstepB, voffB); PG8_STAGE(PG8_SA(1, 0), a3, voffA);
;             PG8_WAIT_V(8); PG8_WAIT_L(0); PG8_BAR; PG8_MMA(1, 0, At, B0); PG8_MMA(1, 1, At, B1); PG8_BAR; PG8_SCHED;
;         }
;         if (wr == 0) PG8_BAR;
	s_add_i32 s0, s0, s20
	v_lshl_add_u64 v[226:227], v[226:227], 0, s[30:31]
	s_mov_b32 m0, s0
	ds_read_b128 v[172:175], v196 offset:49152
	ds_read_b128 v[198:201], v196 offset:50176
	ds_read_b128 v[202:205], v196 offset:51200
	ds_read_b128 v[206:209], v196 offset:52224
	ds_read_b128 v[210:213], v196 offset:53248
	ds_read_b128 v[214:217], v196 offset:54272
	ds_read_b128 v[218:221], v196 offset:55296
	ds_read_b128 v[222:225], v196 offset:56320
	global_load_lds_dwordx4 v[226:227], off
	s_add_i32 m0, s0, 0x2000
	s_add_u32 s6, s6, 0x40080
	v_lshl_add_u64 v[226:227], v[228:229], 0, s[30:31]
	s_addc_u32 s7, s7, 0
	s_add_i32 s0, s26, s20
	global_load_lds_dwordx4 v[226:227], off
	v_lshl_add_u64 v[226:227], s[6:7], 0, v[160:161]
	s_mov_b32 m0, s0
	s_nop 0
	global_load_lds_dwordx4 v[226:227], off
	v_lshl_add_u64 v[226:227], s[6:7], 0, v[162:163]
	s_add_i32 m0, s0, 0x2000
	s_nop 0
	global_load_lds_dwordx4 v[226:227], off
	v_lshl_add_u64 v[226:227], v[230:231], 0, s[30:31]
	s_mov_b32 m0, s24
	s_nop 0
	global_load_lds_dwordx4 v[226:227], off
	v_lshl_add_u64 v[226:227], v[232:233], 0, s[30:31]
	s_mov_b32 m0, s25
	s_nop 0
	global_load_lds_dwordx4 v[226:227], off
	s_waitcnt vmcnt(8)
	s_waitcnt lgkmcnt(0)
	s_barrier
	s_waitcnt lgkmcnt(0)
	v_mfma_f32_16x16x32_bf16 v[60:63], v[128:131], v[172:175], v[60:63]
	v_mfma_f32_16x16x32_bf16 v[56:59], v[136:139], v[172:175], v[56:59]
	v_mfma_f32_16x16x32_bf16 v[44:47], v[128:131], v[202:205], v[44:47]
	v_mfma_f32_16x16x32_bf16 v[40:43], v[136:139], v[202:205], v[40:43]
	v_mfma_f32_16x16x32_bf16 v[28:31], v[128:131], v[210:213], v[28:31]
	v_mfma_f32_16x16x32_bf16 v[24:27], v[136:139], v[210:213], v[24:27]
	v_mfma_f32_16x16x32_bf16 v[12:15], v[128:131], v[218:221], v[12:15]
	v_mfma_f32_16x16x32_bf16 v[8:11], v[136:139], v[218:221], v[8:11]
	v_mfma_f32_16x16x32_bf16 v[60:63], v[132:135], v[198:201], v[60:63]
	v_mfma_f32_16x16x32_bf16 v[56:59], v[140:143], v[198:201], v[56:59]
	v_mfma_f32_16x16x32_bf16 v[44:47], v[132:135], v[206:209], v[44:47]
	v_mfma_f32_16x16x32_bf16 v[40:43], v[140:143], v[206:209], v[40:43]
	v_mfma_f32_16x16x32_bf16 v[28:31], v[132:135], v[214:217], v[28:31]
	v_mfma_f32_16x16x32_bf16 v[24:27], v[140:143], v[214:217], v[24:27]
	v_mfma_f32_16x16x32_bf16 v[12:15], v[132:135], v[222:225], v[12:15]
	v_mfma_f32_16x16x32_bf16 v[8:11], v[140:143], v[222:225], v[8:11]
	v_mfma_f32_16x16x32_bf16 v[52:55], v[144:147], v[172:175], v[52:55]
	v_mfma_f32_16x16x32_bf16 v[48:51], v[152:155], v[172:175], v[48:51]
	v_mfma_f32_16x16x32_bf16 v[36:39], v[144:147], v[202:205], v[36:39]
	v_mfma_f32_16x16x32_bf16 v[32:35], v[152:155], v[202:205], v[32:35]
	v_mfma_f32_16x16x32_bf16 v[20:23], v[144:147], v[210:213], v[20:23]
	v_mfma_f32_16x16x32_bf16 v[16:19], v[152:155], v[210:213], v[16:19]
	v_mfma_f32_16x16x32_bf16 v[4:7], v[144:147], v[218:221], v[4:7]
	v_mfma_f32_16x16x32_bf16 v[0:3], v[152:155], v[218:221], v[0:3]
	v_mfma_f32_16x16x32_bf16 v[52:55], v[148:151], v[198:201], v[52:55]
	v_mfma_f32_16x16x32_bf16 v[48:51], v[168:171], v[198:201], v[48:51]
	v_mfma_f32_16x16x32_bf16 v[36:39], v[148:151], v[206:209], v[36:39]
	v_mfma_f32_16x16x32_bf16 v[32:35], v[168:171], v[206:209], v[32:35]
	v_mfma_f32_16x16x32_bf16 v[20:23], v[148:151], v[214:217], v[20:23]
	v_mfma_f32_16x16x32_bf16 v[16:19], v[168:171], v[214:217], v[16:19]
	v_mfma_f32_16x16x32_bf16 v[4:7], v[148:151], v[222:225], v[4:7]
	v_mfma_f32_16x16x32_bf16 v[0:3], v[168:171], v[222:225], v[0:3]
	s_barrier
	s_add_i32 s54, s54, 2
	s_add_u32 s52, s52, 0x100
	s_addc_u32 s53, s53, 0
	s_add_u32 s33, s33, 0x100
	s_addc_u32 s43, s43, 0
	s_cmp_gt_u32 s54, 13
	s_cbranch_scc0 .LBB0_358
	s_setprio 0
	s_and_b64 vcc, exec, s[18:19]
	s_cbranch_vccz .LBB0_361
	s_barrier

; #define PG8_STAGE(bufoff, gbase, voff) do { _Pragma("unroll") for (int _i = 0; _i < 2; ++_i) \
;         __builtin_amdgcn_global_load_lds((const unsigned*)((const char*)(gbase) + (voff)[_i]), (LAS unsigned*)(lds + (bufoff) + ldsw + _i * 8192), 16, 0, 0); } while (0)
; #define PG8_LDA(dst, b, h) do { _Pragma("unroll") for (int m = 0; m < 4; ++m) _Pragma("unroll") for (int k = 0; k < 2; ++k) dst[m][k] = *(const LAS bf16x8*)(lds + PG8_SA(b, h) + aoff + m * 2048 + k * 1024); } while (0)
; #define PG8_LDB(dst, b, h) do { _Pragma("unroll") for (int n = 0; n < 2; ++n) _Pragma("unroll") for (int k = 0; k < 2; ++k) dst[n][k] = *(const LAS bf16x8*)(lds + PG8_SB(b, h) + boff + n * 2048 + k * 1024); } while (0)
; #define PG8_MMA(ai, bj, At, Bt) do { __builtin_amdgcn_s_setprio(1); _Pragma("unroll") for (int m = 0; m < 4; ++m) _Pragma("unroll") for (int n = 0; n < 2; ++n) _Pragma("unroll") for (int k = 0; k < 2; ++k) \
;         acc[ai][bj][m][n] = __builtin_amdgcn_mfma_f32_16x16x32_bf16(Bt[n][k], At[m][k], acc[ai][bj][m][n], 0, 0, 0); __builtin_amdgcn_s_setprio(0); } while (0)
; #define PG8_BAR __builtin_amdgcn_s_barrier()
; template <class Epi, class Sched>
; __device__ __forceinline__ void gemm_phase(LAS unsigned char* lds, const Gemm g, const Sched& S, const Epi& E) {
;     ...
;         const bool has_next = S.next(ui + 1, nxt);
;         const char* nA = has_next ? (const char*)g.A + (size_t)nxt.pm * tstepA + (size_t)nxt.pn * apn : cA; const char* nB = has_next ? (const char*)g.Bt + (size_t)nxt.pn * tstepB : cB;
;         for (int t = 0; t < nt; t += 2) {
;             const bool last = (t == nt - 2);
;             const char* a1 = cA + (size_t)(t + 1) * kstep;
;             const char* a2 = last ? nA : cA + (size_t)(t + 2) * kstep; const char* b2 = last ? nB : cB + (size_t)(t + 2) * kstep;
;             const char* a3 = a2 + kstep; const char* b3 = b2 + kstep;
;             PG8_LDB(B0, 0, 0); PG8_LDB(B1, 0, 1); PG8_SCHED; PG8_LDA(At, 0, 0); PG8_STAGE(PG8_SA(1, 1), a1 + hstepA, voffA);
;             PG8_WAIT_V(8); PG8_WAIT_L(0); PG8_BAR; PG8_MMA(0, 0, At, B0); PG8_MMA(0, 1, At, B1); PG8_BAR; PG8_SCHED;
;             PG8_LDA(At, 0, 1); PG8_STAGE(PG8_SB(0, 0), b2, voffB); PG8_STAGE(PG8_SB(0, 1), b2 + hstepB, voffB); PG8_STAGE(PG8_SA(0, 0), a2, voffA);
;             PG8_WAIT_V(8); PG8_WAIT_L(0); PG8_BAR; PG8_MMA(1, 0, At, B0); PG8_MMA(1, 1, At, B1); PG8_BAR; PG8_SCHED;
.LBB0_627:
	s_lshl_b64 s[6:7], s[22:23], 17
	s_add_u32 s46, s28, s6
	s_addc_u32 s47, s20, s7
	s_and_b64 s[6:7], exec, s[42:43]
	s_cselect_b32 s9, s47, s51
	s_cselect_b32 s13, s46, s50
	s_mov_b32 s6, 0
	s_mov_b64 s[54:55], -1
	s_mov_b64 s[56:57], 0
	s_waitcnt lgkmcnt(0)
	s_cmp_eq_u64 s[18:19], 0
	s_cbranch_scc0 .Lprio_628
	s_setprio 1
.Lprio_628:
	s_add_u32 s0, s52, s6
	s_addc_u32 s23, s53, 0
	s_add_u32 s7, s0, 0x100
	s_addc_u32 s26, s23, 0
	s_and_b64 s[14:15], s[56:57], exec
	s_cselect_b32 vcc_hi, s45, s26
	s_cselect_b32 vcc_lo, s44, s7
	s_add_u32 s6, s50, s6
	s_addc_u32 s7, s51, 0
	s_add_u32 s14, s6, 0x100
	s_addc_u32 s15, s7, 0
	s_add_i32 s80, 0, 0x10000
	s_and_b64 s[6:7], s[56:57], exec
	s_cselect_b32 s7, s9, s15
	s_cselect_b32 s6, s13, s14
	s_add_i32 s57, 0, 0x14000
	s_add_u32 s78, s0, 0x40080
	s_addc_u32 s79, s23, 0
	s_add_i32 s97, s80, s24
	s_add_i32 m0, s25, 0xc000
	s_add_i32 s81, s25, 0xe000
	s_add_i32 s88, s97, 0x2000
	s_add_u32 s14, s6, 0x10000
	v_add_u32_e32 v140, s80, v174
	v_add_u32_e32 v164, s57, v174
	s_addc_u32 s15, s7, 0
	s_add_i32 s89, s57, s24
	ds_read_b128 v[128:131], v140
	ds_read_b128 v[132:135], v140 offset:1024
	ds_read_b128 v[136:139], v140 offset:2048
	ds_read_b128 v[140:143], v140 offset:3072
	ds_read_b128 v[144:147], v164
	ds_read_b128 v[148:151], v164 offset:1024
	ds_read_b128 v[152:155], v164 offset:2048
	ds_read_b128 v[164:167], v164 offset:3072
	s_add_i32 s96, s89, 0x2000
	s_add_i32 s35, 0, 0x18000
	s_add_i32 s0, 0, 0x1c000
	s_add_u32 s68, vcc_lo, 0x40000
	s_addc_u32 s69, vcc_hi, 0
	s_add_i32 s23, s35, s24
	s_add_i32 s26, s23, 0x2000
	s_add_u32 s56, s6, 0x10080
	s_addc_u32 s57, s7, 0
	s_add_i32 s83, s0, s24
	s_add_i32 s80, s83, 0x2000
	v_lshl_add_u64 v[192:193], s[78:79], 0, v[156:157]
	ds_read_b128 v[168:171], v191
	ds_read_b128 v[196:199], v191 offset:1024
	ds_read_b128 v[200:203], v191 offset:2048
	ds_read_b128 v[204:207], v191 offset:3072
	ds_read_b128 v[208:211], v191 offset:4096
	ds_read_b128 v[212:215], v191 offset:5120
	ds_read_b128 v[216:219], v191 offset:6144
	ds_read_b128 v[220:223], v191 offset:7168
	global_load_lds_dwordx4 v[192:193], off
	v_lshl_add_u64 v[192:193], s[78:79], 0, v[158:159]
	s_mov_b32 m0, s81
	s_nop 0
	global_load_lds_dwordx4 v[192:193], off
	s_waitcnt vmcnt(8)
	s_waitcnt lgkmcnt(0)
	s_barrier
	s_waitcnt lgkmcnt(0)
	v_mfma_f32_16x16x32_bf16 v[124:127], v[128:131], v[168:171], 0
	v_mfma_f32_16x16x32_bf16 v[120:123], v[136:139], v[168:171], 0
	v_mfma_f32_16x16x32_bf16 v[108:111], v[128:131], v[200:203], 0
	v_mfma_f32_16x16x32_bf16 v[104:107], v[136:139], v[200:203], 0
	v_mfma_f32_16x16x32_bf16 v[92:95], v[128:131], v[208:211], 0
	v_mfma_f32_16x16x32_bf16 v[88:91], v[136:139], v[208:211], 0
	v_mfma_f32_16x16x32_bf16 v[76:79], v[128:131], v[216:219], 0
	v_mfma_f32_16x16x32_bf16 v[72:75], v[136:139], v[216:219], 0
	v_mfma_f32_16x16x32_bf16 v[124:127], v[132:135], v[196:199], v[124:127]
	v_mfma_f32_16x16x32_bf16 v[120:123], v[140:143], v[196:199], v[120:123]
	v_mfma_f32_16x16x32_bf16 v[108:111], v[132:135], v[204:207], v[108:111]
	v_mfma_f32_16x16x32_bf16 v[104:107], v[140:143], v[204:207], v[104:107]
	v_mfma_f32_16x16x32_bf16 v[92:95], v[132:135], v[212:215], v[92:95]
	v_mfma_f32_16x16x32_bf16 v[88:91], v[140:143], v[212:215], v[88:91]
	v_mfma_f32_16x16x32_bf16 v[76:79], v[132:135], v[220:223], v[76:79]
	v_mfma_f32_16x16x32_bf16 v[72:75], v[140:143], v[220:223], v[72:75]
	v_mfma_f32_16x16x32_bf16 v[116:119], v[144:147], v[168:171], 0
	v_mfma_f32_16x16x32_bf16 v[112:115], v[152:155], v[168:171], 0
	v_mfma_f32_16x16x32_bf16 v[100:103], v[144:147], v[200:203], 0
	v_mfma_f32_16x16x32_bf16 v[96:99], v[152:155], v[200:203], 0
	v_mfma_f32_16x16x32_bf16 v[84:87], v[144:147], v[208:211], 0
	v_mfma_f32_16x16x32_bf16 v[80:83], v[152:155], v[208:211], 0
	v_mfma_f32_16x16x32_bf16 v[68:71], v[144:147], v[216:219], 0
	v_mfma_f32_16x16x32_bf16 v[64:67], v[152:155], v[216:219], 0
	v_mfma_f32_16x16x32_bf16 v[116:119], v[148:151], v[196:199], v[116:119]
	v_mfma_f32_16x16x32_bf16 v[112:115], v[164:167], v[196:199], v[112:115]
	v_mfma_f32_16x16x32_bf16 v[100:103], v[148:151], v[204:207], v[100:103]
	v_mfma_f32_16x16x32_bf16 v[96:99], v[164:167], v[204:207], v[96:99]
	v_mfma_f32_16x16x32_bf16 v[84:87], v[148:151], v[212:215], v[84:87]
	v_mfma_f32_16x16x32_bf16 v[80:83], v[164:167], v[212:215], v[80:83]
	v_mfma_f32_16x16x32_bf16 v[68:71], v[148:151], v[220:223], v[68:71]
	v_mfma_f32_16x16x32_bf16 v[64:67], v[164:167], v[220:223], v[64:67]
	s_barrier
	s_mov_b32 m0, s97
	v_lshl_add_u64 v[192:193], s[6:7], 0, v[160:161]
	ds_read_b128 v[168:171], v191 offset:16384
	ds_read_b128 v[196:199], v191 offset:17408
	ds_read_b128 v[200:203], v191 offset:18432
	ds_read_b128 v[204:207], v191 offset:19456
	ds_read_b128 v[208:211], v191 offset:20480
	ds_read_b128 v[212:215], v191 offset:21504
	ds_read_b128 v[216:219], v191 offset:22528
	ds_read_b128 v[220:223], v191 offset:23552
	global_load_lds_dwordx4 v[192:193], off
	v_lshl_add_u64 v[224:225], s[6:7], 0, v[162:163]
	s_mov_b32 m0, s88
	v_lshl_add_u64 v[226:227], s[14:15], 0, v[160:161]
	global_load_lds_dwordx4 v[224:225], off
	s_mov_b32 m0, s89
	v_lshl_add_u64 v[228:229], vcc, 0, v[158:159]
	global_load_lds_dwordx4 v[226:227], off
	v_lshl_add_u64 v[226:227], s[14:15], 0, v[162:163]
	s_mov_b32 m0, s96
	s_nop 0
	global_load_lds_dwordx4 v[226:227], off
	v_lshl_add_u64 v[226:227], vcc, 0, v[156:157]
	s_mov_b32 m0, s25
	s_nop 0
	global_load_lds_dwordx4 v[226:227], off
	s_mov_b32 m0, s49
	s_nop 0
	global_load_lds_dwordx4 v[228:229], off
	s_waitcnt vmcnt(8)
	s_waitcnt lgkmcnt(0)
	s_barrier
; #define PG8_STAGE(bufoff, gbase, voff) do { _Pragma("unroll") for (int _i = 0; _i < 2; ++_i) \
;         __builtin_amdgcn_global_load_lds((const unsigned*)((const char*)(gbase) + (voff)[_i]), (LAS unsigned*)(lds + (bufoff) + ldsw + _i * 8192), 16, 0, 0); } while (0)
; #define PG8_LDA(dst, b, h) do { _Pragma("unroll") for (int m = 0; m < 4; ++m) _Pragma("unroll") for (int k = 0; k < 2; ++k) dst[m][k] = *(const LAS bf16x8*)(lds + PG8_SA(b, h) + aoff + m * 2048 + k * 1024); } while (0)
; #define PG8_LDB(dst, b, h) do { _Pragma("unroll") for (int n = 0; n < 2; ++n) _Pragma("unroll") for (int k = 0; k < 2; ++k) dst[n][k] = *(const LAS bf16x8*)(lds + PG8_SB(b, h) + boff + n * 2048 + k * 1024); } while (0)
; #define PG8_MMA(ai, bj, At, Bt) do { __builtin_amdgcn_s_setprio(1); _Pragma("unroll") for (int m = 0; m < 4; ++m) _Pragma("unroll") for (int n = 0; n < 2; ++n) _Pragma("unroll") for (int k = 0; k < 2; ++k) \
;         acc[ai][bj][m][n] = __builtin_amdgcn_mfma_f32_16x16x32_bf16(Bt[n][k], At[m][k], acc[ai][bj][m][n], 0, 0, 0); __builtin_amdgcn_s_setprio(0); } while (0)
; #define PG8_WAIT_V(n) asm volatile("s_waitcnt vmcnt(" #n ")" ::: "memory")
; #define PG8_WAIT_L(n) asm volatile("s_waitcnt lgkmcnt(" #n ")" ::: "memory")
; #define PG8_BAR __builtin_amdgcn_s_barrier()
; #define PG8_SCHED __builtin_amdgcn_sched_barrier(0)
; template <class Epi, class Sched>
; __device__ __forceinline__ void gemm_phase(LAS unsigned char* lds, const Gemm g, const Sched& S, const Epi& E) {
;     ...
;             PG8_WAIT_V(8); PG8_WAIT_L(0); PG8_BAR; PG8_MMA(1, 0, At, B0); PG8_MMA(1, 1, At, B1); PG8_BAR; PG8_SCHED;
;             PG8_LDB(B0, 1, 0); PG8_LDB(B1, 1, 1); PG8_SCHED; PG8_LDA(At, 1, 0); PG8_STAGE(PG8_SA(0, 1), a2 + hstepA, voffA);
;             PG8_WAIT_V(8); PG8_WAIT_L(0); PG8_BAR; PG8_MMA(0, 0, At, B0); PG8_MMA(0, 1, At, B1); PG8_BAR; PG8_SCHED;
	s_waitcnt lgkmcnt(0)
	v_mfma_f32_16x16x32_bf16 v[60:63], v[128:131], v[168:171], 0
	v_mfma_f32_16x16x32_bf16 v[56:59], v[136:139], v[168:171], 0
	v_mfma_f32_16x16x32_bf16 v[44:47], v[128:131], v[200:203], 0
	v_mfma_f32_16x16x32_bf16 v[40:43], v[136:139], v[200:203], 0
	v_mfma_f32_16x16x32_bf16 v[28:31], v[128:131], v[208:211], 0
	v_mfma_f32_16x16x32_bf16 v[24:27], v[136:139], v[208:211], 0
	v_mfma_f32_16x16x32_bf16 v[12:15], v[128:131], v[216:219], 0
	v_mfma_f32_16x16x32_bf16 v[8:11], v[136:139], v[216:219], 0
	v_mfma_f32_16x16x32_bf16 v[60:63], v[132:135], v[196:199], v[60:63]
	v_mfma_f32_16x16x32_bf16 v[56:59], v[140:143], v[196:199], v[56:59]
	v_mfma_f32_16x16x32_bf16 v[44:47], v[132:135], v[204:207], v[44:47]
	v_mfma_f32_16x16x32_bf16 v[40:43], v[140:143], v[204:207], v[40:43]
	v_mfma_f32_16x16x32_bf16 v[28:31], v[132:135], v[212:215], v[28:31]
	v_mfma_f32_16x16x32_bf16 v[24:27], v[140:143], v[212:215], v[24:27]
	v_mfma_f32_16x16x32_bf16 v[12:15], v[132:135], v[220:223], v[12:15]
	v_mfma_f32_16x16x32_bf16 v[8:11], v[140:143], v[220:223], v[8:11]
	v_mfma_f32_16x16x32_bf16 v[52:55], v[144:147], v[168:171], 0
	v_mfma_f32_16x16x32_bf16 v[48:51], v[152:155], v[168:171], 0
	v_mfma_f32_16x16x32_bf16 v[36:39], v[144:147], v[200:203], 0
	v_mfma_f32_16x16x32_bf16 v[32:35], v[152:155], v[200:203], 0
	v_mfma_f32_16x16x32_bf16 v[20:23], v[144:147], v[208:211], 0
	v_mfma_f32_16x16x32_bf16 v[16:19], v[152:155], v[208:211], 0
	v_mfma_f32_16x16x32_bf16 v[4:7], v[144:147], v[216:219], 0
	v_mfma_f32_16x16x32_bf16 v[0:3], v[152:155], v[216:219], 0
	v_mfma_f32_16x16x32_bf16 v[52:55], v[148:151], v[196:199], v[52:55]
	v_mfma_f32_16x16x32_bf16 v[48:51], v[164:167], v[196:199], v[48:51]
	v_mfma_f32_16x16x32_bf16 v[36:39], v[148:151], v[204:207], v[36:39]
	v_mfma_f32_16x16x32_bf16 v[32:35], v[164:167], v[204:207], v[32:35]
	v_mfma_f32_16x16x32_bf16 v[20:23], v[148:151], v[212:215], v[20:23]
	v_mfma_f32_16x16x32_bf16 v[16:19], v[164:167], v[212:215], v[16:19]
	v_mfma_f32_16x16x32_bf16 v[4:7], v[148:151], v[220:223], v[4:7]
	v_mfma_f32_16x16x32_bf16 v[0:3], v[164:167], v[220:223], v[0:3]
	s_barrier
	v_add_u32_e32 v140, s35, v174
	v_add_u32_e32 v164, s0, v174
	ds_read_b128 v[128:131], v140
	ds_read_b128 v[132:135], v140 offset:1024
	ds_read_b128 v[136:139], v140 offset:2048
	ds_read_b128 v[140:143], v140 offset:3072
	ds_read_b128 v[144:147], v164
	ds_read_b128 v[148:151], v164 offset:1024
	ds_read_b128 v[152:155], v164 offset:2048
	ds_read_b128 v[164:167], v164 offset:3072
	s_mov_b32 m0, s82
	v_lshl_add_u64 v[230:231], s[68:69], 0, v[156:157]
	ds_read_b128 v[168:171], v191 offset:32768
	ds_read_b128 v[196:199], v191 offset:33792
	ds_read_b128 v[200:203], v191 offset:34816
	ds_read_b128 v[204:207], v191 offset:35840
	ds_read_b128 v[208:211], v191 offset:36864
	ds_read_b128 v[212:215], v191 offset:37888
	ds_read_b128 v[216:219], v191 offset:38912
	ds_read_b128 v[220:223], v191 offset:39936
	global_load_lds_dwordx4 v[230:231], off
	v_lshl_add_u64 v[230:231], s[68:69], 0, v[158:159]
	s_mov_b32 m0, s33
	s_nop 0
	global_load_lds_dwordx4 v[230:231], off
	s_waitcnt vmcnt(8)
	s_waitcnt lgkmcnt(0)
	s_barrier
	s_waitcnt lgkmcnt(0)
	v_mfma_f32_16x16x32_bf16 v[124:127], v[128:131], v[168:171], v[124:127]
	v_mfma_f32_16x16x32_bf16 v[120:123], v[136:139], v[168:171], v[120:123]
	v_mfma_f32_16x16x32_bf16 v[108:111], v[128:131], v[200:203], v[108:111]
	v_mfma_f32_16x16x32_bf16 v[104:107], v[136:139], v[200:203], v[104:107]
	v_mfma_f32_16x16x32_bf16 v[92:95], v[128:131], v[208:211], v[92:95]
	v_mfma_f32_16x16x32_bf16 v[88:91], v[136:139], v[208:211], v[88:91]
	v_mfma_f32_16x16x32_bf16 v[76:79], v[128:131], v[216:219], v[76:79]
	v_mfma_f32_16x16x32_bf16 v[72:75], v[136:139], v[216:219], v[72:75]
	v_mfma_f32_16x16x32_bf16 v[124:127], v[132:135], v[196:199], v[124:127]
	v_mfma_f32_16x16x32_bf16 v[120:123], v[140:143], v[196:199], v[120:123]
	v_mfma_f32_16x16x32_bf16 v[108:111], v[132:135], v[204:207], v[108:111]
	v_mfma_f32_16x16x32_bf16 v[104:107], v[140:143], v[204:207], v[104:107]
	v_mfma_f32_16x16x32_bf16 v[92:95], v[132:135], v[212:215], v[92:95]
	v_mfma_f32_16x16x32_bf16 v[88:91], v[140:143], v[212:215], v[88:91]
	v_mfma_f32_16x16x32_bf16 v[76:79], v[132:135], v[220:223], v[76:79]
	v_mfma_f32_16x16x32_bf16 v[72:75], v[140:143], v[220:223], v[72:75]
	v_mfma_f32_16x16x32_bf16 v[116:119], v[144:147], v[168:171], v[116:119]
	v_mfma_f32_16x16x32_bf16 v[112:115], v[152:155], v[168:171], v[112:115]
	v_mfma_f32_16x16x32_bf16 v[100:103], v[144:147], v[200:203], v[100:103]
	v_mfma_f32_16x16x32_bf16 v[96:99], v[152:155], v[200:203], v[96:99]
	v_mfma_f32_16x16x32_bf16 v[84:87], v[144:147], v[208:211], v[84:87]
	v_mfma_f32_16x16x32_bf16 v[80:83], v[152:155], v[208:211], v[80:83]
	v_mfma_f32_16x16x32_bf16 v[68:71], v[144:147], v[216:219], v[68:71]
	v_mfma_f32_16x16x32_bf16 v[64:67], v[152:155], v[216:219], v[64:67]
	v_mfma_f32_16x16x32_bf16 v[116:119], v[148:151], v[196:199], v[116:119]
	v_mfma_f32_16x16x32_bf16 v[112:115], v[164:167], v[196:199], v[112:115]
	v_mfma_f32_16x16x32_bf16 v[100:103], v[148:151], v[204:207], v[100:103]
	v_mfma_f32_16x16x32_bf16 v[96:99], v[164:167], v[204:207], v[96:99]
	v_mfma_f32_16x16x32_bf16 v[84:87], v[148:151], v[212:215], v[84:87]
	v_mfma_f32_16x16x32_bf16 v[80:83], v[164:167], v[212:215], v[80:83]
	v_mfma_f32_16x16x32_bf16 v[68:71], v[148:151], v[220:223], v[68:71]
	v_mfma_f32_16x16x32_bf16 v[64:67], v[164:167], v[220:223], v[64:67]
	s_barrier
; #define PG8_STAGE(bufoff, gbase, voff) do { _Pragma("unroll") for (int _i = 0; _i < 2; ++_i) \
;         __builtin_amdgcn_global_load_lds((const unsigned*)((const char*)(gbase) + (voff)[_i]), (LAS unsigned*)(lds + (bufoff) + ldsw + _i * 8192), 16, 0, 0); } while (0)
; #define PG8_LDA(dst, b, h) do { _Pragma("unroll") for (int m = 0; m < 4; ++m) _Pragma("unroll") for (int k = 0; k < 2; ++k) dst[m][k] = *(const LAS bf16x8*)(lds + PG8_SA(b, h) + aoff + m * 2048 + k * 1024); } while (0)
; #define PG8_LDB(dst, b, h) do { _Pragma("unroll") for (int n = 0; n < 2; ++n) _Pragma("unroll") for (int k = 0; k < 2; ++k) dst[n][k] = *(const LAS bf16x8*)(lds + PG8_SB(b, h) + boff + n * 2048 + k * 1024); } while (0)
; #define PG8_MMA(ai, bj, At, Bt) do { __builtin_amdgcn_s_setprio(1); _Pragma("unroll") for (int m = 0; m < 4; ++m) _Pragma("unroll") for (int n = 0; n < 2; ++n) _Pragma("unroll") for (int k = 0; k < 2; ++k) \
;         acc[ai][bj][m][n] = __builtin_amdgcn_mfma_f32_16x16x32_bf16(Bt[n][k], At[m][k], acc[ai][bj][m][n], 0, 0, 0); __builtin_amdgcn_s_setprio(0); } while (0)
; #define PG8_BAR __builtin_amdgcn_s_barrier()
; template <class Epi, class Sched>
; __device__ __forceinline__ void gemm_phase(LAS unsigned char* lds, const Gemm g, const Sched& S, const Epi& E) {
;     ...
;         const bool has_next = S.next(ui + 1, nxt);
;         const char* nA = has_next ? (const char*)g.A + (size_t)nxt.pm * tstepA + (size_t)nxt.pn * apn : cA; const char* nB = has_next ? (const char*)g.Bt + (size_t)nxt.pn * tstepB : cB;
;         for (int t = 0; t < nt; t += 2) {
;             const bool last = (t == nt - 2);
;             const char* a1 = cA + (size_t)(t + 1) * kstep;
;             const char* a2 = last ? nA : cA + (size_t)(t + 2) * kstep; const char* b2 = last ? nB : cB + (size_t)(t + 2) * kstep;
;             const char* a3 = a2 + kstep; const char* b3 = b2 + kstep;
;             PG8_LDB(B0, 0, 0); PG8_LDB(B1, 0, 1); PG8_SCHED; PG8_LDA(At, 0, 0); PG8_STAGE(PG8_SA(1, 1), a1 + hstepA, voffA);
;             PG8_WAIT_V(8); PG8_WAIT_L(0); PG8_BAR; PG8_MMA(0, 0, At, B0); PG8_MMA(0, 1, At, B1); PG8_BAR; PG8_SCHED;
;     ...
;             PG8_LDA(At, 1, 1); PG8_STAGE(PG8_SB(1, 0), b3, voffB); PG8_STAGE(PG8_SB(1, 1), b3 + hstepB, voffB); PG8_STAGE(PG8_SA(1, 0), a3, voffA);
;             PG8_WAIT_V(8); PG8_WAIT_L(0); PG8_BAR; PG8_MMA(1, 0, At, B0); PG8_MMA(1, 1, At, B1); PG8_BAR; PG8_SCHED;
	s_mov_b32 m0, s23
	v_lshl_add_u64 v[192:193], v[192:193], 0, s[30:31]
	ds_read_b128 v[168:171], v191 offset:49152
	ds_read_b128 v[196:199], v191 offset:50176
	ds_read_b128 v[200:203], v191 offset:51200
	ds_read_b128 v[204:207], v191 offset:52224
	ds_read_b128 v[208:211], v191 offset:53248
	ds_read_b128 v[212:215], v191 offset:54272
	ds_read_b128 v[216:219], v191 offset:55296
	ds_read_b128 v[220:223], v191 offset:56320
	global_load_lds_dwordx4 v[192:193], off
	v_lshl_add_u64 v[192:193], v[224:225], 0, s[30:31]
	s_mov_b32 m0, s26
	s_nop 0
	global_load_lds_dwordx4 v[192:193], off
	v_lshl_add_u64 v[192:193], s[56:57], 0, v[160:161]
	s_mov_b32 m0, s83
	s_nop 0
	global_load_lds_dwordx4 v[192:193], off
	v_lshl_add_u64 v[192:193], s[56:57], 0, v[162:163]
	s_mov_b32 m0, s80
	s_nop 0
	global_load_lds_dwordx4 v[192:193], off
	v_lshl_add_u64 v[192:193], v[226:227], 0, s[30:31]
	s_mov_b32 m0, s90
	s_nop 0
	global_load_lds_dwordx4 v[192:193], off
	v_lshl_add_u64 v[192:193], v[228:229], 0, s[30:31]
	s_mov_b32 m0, s21
	s_nop 0
	global_load_lds_dwordx4 v[192:193], off
	s_waitcnt vmcnt(8)
	s_waitcnt lgkmcnt(0)
	s_barrier
	s_waitcnt lgkmcnt(0)
	v_mfma_f32_16x16x32_bf16 v[60:63], v[128:131], v[168:171], v[60:63]
	v_mfma_f32_16x16x32_bf16 v[56:59], v[136:139], v[168:171], v[56:59]
	v_mfma_f32_16x16x32_bf16 v[44:47], v[128:131], v[200:203], v[44:47]
	v_mfma_f32_16x16x32_bf16 v[40:43], v[136:139], v[200:203], v[40:43]
	v_mfma_f32_16x16x32_bf16 v[28:31], v[128:131], v[208:211], v[28:31]
	v_mfma_f32_16x16x32_bf16 v[24:27], v[136:139], v[208:211], v[24:27]
	v_mfma_f32_16x16x32_bf16 v[12:15], v[128:131], v[216:219], v[12:15]
	v_mfma_f32_16x16x32_bf16 v[8:11], v[136:139], v[216:219], v[8:11]
	v_mfma_f32_16x16x32_bf16 v[60:63], v[132:135], v[196:199], v[60:63]
	v_mfma_f32_16x16x32_bf16 v[56:59], v[140:143], v[196:199], v[56:59]
	v_mfma_f32_16x16x32_bf16 v[44:47], v[132:135], v[204:207], v[44:47]
	v_mfma_f32_16x16x32_bf16 v[40:43], v[140:143], v[204:207], v[40:43]
	v_mfma_f32_16x16x32_bf16 v[28:31], v[132:135], v[212:215], v[28:31]
	v_mfma_f32_16x16x32_bf16 v[24:27], v[140:143], v[212:215], v[24:27]
	v_mfma_f32_16x16x32_bf16 v[12:15], v[132:135], v[220:223], v[12:15]
	v_mfma_f32_16x16x32_bf16 v[8:11], v[140:143], v[220:223], v[8:11]
	v_mfma_f32_16x16x32_bf16 v[52:55], v[144:147], v[168:171], v[52:55]
	v_mfma_f32_16x16x32_bf16 v[48:51], v[152:155], v[168:171], v[48:51]
	v_mfma_f32_16x16x32_bf16 v[36:39], v[144:147], v[200:203], v[36:39]
	v_mfma_f32_16x16x32_bf16 v[32:35], v[152:155], v[200:203], v[32:35]
	v_mfma_f32_16x16x32_bf16 v[20:23], v[144:147], v[208:211], v[20:23]
	v_mfma_f32_16x16x32_bf16 v[16:19], v[152:155], v[208:211], v[16:19]
	v_mfma_f32_16x16x32_bf16 v[4:7], v[144:147], v[216:219], v[4:7]
	v_mfma_f32_16x16x32_bf16 v[0:3], v[152:155], v[216:219], v[0:3]
	v_mfma_f32_16x16x32_bf16 v[52:55], v[148:151], v[196:199], v[52:55]
	v_mfma_f32_16x16x32_bf16 v[48:51], v[164:167], v[196:199], v[48:51]
	v_mfma_f32_16x16x32_bf16 v[36:39], v[148:151], v[204:207], v[36:39]
	v_mfma_f32_16x16x32_bf16 v[32:35], v[164:167], v[204:207], v[32:35]
	v_mfma_f32_16x16x32_bf16 v[20:23], v[148:151], v[212:215], v[20:23]
	v_mfma_f32_16x16x32_bf16 v[16:19], v[164:167], v[212:215], v[16:19]
	v_mfma_f32_16x16x32_bf16 v[4:7], v[148:151], v[220:223], v[4:7]
	v_mfma_f32_16x16x32_bf16 v[0:3], v[164:167], v[220:223], v[0:3]
	s_barrier
	s_movk_i32 s6, 0x100
	s_andn2_b64 vcc, exec, s[54:55]
	s_mov_b64 s[56:57], -1
	s_mov_b64 s[54:55], 0
.LBB0_628:
	s_add_u32 s0, s52, s6
	s_addc_u32 s23, s53, 0
	s_add_u32 s7, s0, 0x100
	s_addc_u32 s26, s23, 0
	s_and_b64 s[14:15], s[56:57], exec
	s_cselect_b32 vcc_hi, s45, s26
	s_cselect_b32 vcc_lo, s44, s7
	s_add_u32 s6, s50, s6
	s_addc_u32 s7, s51, 0
	s_add_u32 s14, s6, 0x100
	s_addc_u32 s15, s7, 0
	s_add_i32 s80, 0, 0x10000
	s_and_b64 s[6:7], s[56:57], exec
	s_cselect_b32 s7, s9, s15
	s_cselect_b32 s6, s13, s14
	s_add_i32 s57, 0, 0x14000
	s_add_u32 s78, s0, 0x40080
	s_addc_u32 s79, s23, 0
	s_add_i32 s97, s80, s24
	s_add_i32 m0, s25, 0xc000
	s_add_i32 s81, s25, 0xe000
	s_add_i32 s88, s97, 0x2000
	s_add_u32 s14, s6, 0x10000
	v_add_u32_e32 v140, s80, v174
	v_add_u32_e32 v164, s57, v174
	s_addc_u32 s15, s7, 0
	s_add_i32 s89, s57, s24
	ds_read_b128 v[128:131], v140
	ds_read_b128 v[132:135], v140 offset:1024
	ds_read_b128 v[136:139], v140 offset:2048
	ds_read_b128 v[140:143], v140 offset:3072
	ds_read_b128 v[144:147], v164
	ds_read_b128 v[148:151], v164 offset:1024
	ds_read_b128 v[152:155], v164 offset:2048
	ds_read_b128 v[164:167], v164 offset:3072
	s_add_i32 s96, s89, 0x2000
	s_add_i32 s35, 0, 0x18000
	s_add_i32 s0, 0, 0x1c000
	s_add_u32 s68, vcc_lo, 0x40000
	s_addc_u32 s69, vcc_hi, 0
	s_add_i32 s23, s35, s24
	s_add_i32 s26, s23, 0x2000
	s_add_u32 s56, s6, 0x10080
	s_addc_u32 s57, s7, 0
	s_add_i32 s83, s0, s24
	s_add_i32 s80, s83, 0x2000
	v_lshl_add_u64 v[192:193], s[78:79], 0, v[156:157]
	ds_read_b128 v[168:171], v191
	ds_read_b128 v[196:199], v191 offset:1024
	ds_read_b128 v[200:203], v191 offset:2048
	ds_read_b128 v[204:207], v191 offset:3072
	ds_read_b128 v[208:211], v191 offset:4096
	ds_read_b128 v[212:215], v191 offset:5120
	ds_read_b128 v[216:219], v191 offset:6144
	ds_read_b128 v[220:223], v191 offset:7168
	global_load_lds_dwordx4 v[192:193], off
	v_lshl_add_u64 v[192:193], s[78:79], 0, v[158:159]
	s_mov_b32 m0, s81
	s_nop 0
	global_load_lds_dwordx4 v[192:193], off
	s_waitcnt vmcnt(8)
	s_waitcnt lgkmcnt(0)
	s_barrier
; #define PG8_STAGE(bufoff, gbase, voff) do { _Pragma("unroll") for (int _i = 0; _i < 2; ++_i) \
;         __builtin_amdgcn_global_load_lds((const unsigned*)((const char*)(gbase) + (voff)[_i]), (LAS unsigned*)(lds + (bufoff) + ldsw + _i * 8192), 16, 0, 0); } while (0)
; #define PG8_LDA(dst, b, h) do { _Pragma("unroll") for (int m = 0; m < 4; ++m) _Pragma("unroll") for (int k = 0; k < 2; ++k) dst[m][k] = *(const LAS bf16x8*)(lds + PG8_SA(b, h) + aoff + m * 2048 + k * 1024); } while (0)
; #define PG8_LDB(dst, b, h) do { _Pragma("unroll") for (int n = 0; n < 2; ++n) _Pragma("unroll") for (int k = 0; k < 2; ++k) dst[n][k] = *(const LAS bf16x8*)(lds + PG8_SB(b, h) + boff + n * 2048 + k * 1024); } while (0)
; #define PG8_MMA(ai, bj, At, Bt) do { __builtin_amdgcn_s_setprio(1); _Pragma("unroll") for (int m = 0; m < 4; ++m) _Pragma("unroll") for (int n = 0; n < 2; ++n) _Pragma("unroll") for (int k = 0; k < 2; ++k) \
;         acc[ai][bj][m][n] = __builtin_amdgcn_mfma_f32_16x16x32_bf16(Bt[n][k], At[m][k], acc[ai][bj][m][n], 0, 0, 0); __builtin_amdgcn_s_setprio(0); } while (0)
; #define PG8_WAIT_V(n) asm volatile("s_waitcnt vmcnt(" #n ")" ::: "memory")
; #define PG8_WAIT_L(n) asm volatile("s_waitcnt lgkmcnt(" #n ")" ::: "memory")
; #define PG8_BAR __builtin_amdgcn_s_barrier()
; #define PG8_SCHED __builtin_amdgcn_sched_barrier(0)
; template <class Epi, class Sched>
; __device__ __forceinline__ void gemm_phase(LAS unsigned char* lds, const Gemm g, const Sched& S, const Epi& E) {
;     ...
;             PG8_WAIT_V(8); PG8_WAIT_L(0); PG8_BAR; PG8_MMA(0, 0, At, B0); PG8_MMA(0, 1, At, B1); PG8_BAR; PG8_SCHED;
;             PG8_LDA(At, 0, 1); PG8_STAGE(PG8_SB(0, 0), b2, voffB); PG8_STAGE(PG8_SB(0, 1), b2 + hstepB, voffB); PG8_STAGE(PG8_SA(0, 0), a2, voffA);
;             PG8_WAIT_V(8); PG8_WAIT_L(0); PG8_BAR; PG8_MMA(1, 0, At, B0); PG8_MMA(1, 1, At, B1); PG8_BAR; PG8_SCHED;
;             PG8_LDB(B0, 1, 0); PG8_LDB(B1, 1, 1); PG8_SCHED; PG8_LDA(At, 1, 0); PG8_STAGE(PG8_SA(0, 1), a2 + hstepA, voffA);
;             PG8_WAIT_V(8); PG8_WAIT_L(0); PG8_BAR; PG8_MMA(0, 0, At, B0); PG8_MMA(0, 1, At, B1); PG8_BAR; PG8_SCHED;
	s_waitcnt lgkmcnt(0)
	v_mfma_f32_16x16x32_bf16 v[124:127], v[128:131], v[168:171], v[124:127]
	v_mfma_f32_16x16x32_bf16 v[120:123], v[136:139], v[168:171], v[120:123]
	v_mfma_f32_16x16x32_bf16 v[108:111], v[128:131], v[200:203], v[108:111]
	v_mfma_f32_16x16x32_bf16 v[104:107], v[136:139], v[200:203], v[104:107]
	v_mfma_f32_16x16x32_bf16 v[92:95], v[128:131], v[208:211], v[92:95]
	v_mfma_f32_16x16x32_bf16 v[88:91], v[136:139], v[208:211], v[88:91]
	v_mfma_f32_16x16x32_bf16 v[76:79], v[128:131], v[216:219], v[76:79]
	v_mfma_f32_16x16x32_bf16 v[72:75], v[136:139], v[216:219], v[72:75]
	v_mfma_f32_16x16x32_bf16 v[124:127], v[132:135], v[196:199], v[124:127]
	v_mfma_f32_16x16x32_bf16 v[120:123], v[140:143], v[196:199], v[120:123]
	v_mfma_f32_16x16x32_bf16 v[108:111], v[132:135], v[204:207], v[108:111]
	v_mfma_f32_16x16x32_bf16 v[104:107], v[140:143], v[204:207], v[104:107]
	v_mfma_f32_16x16x32_bf16 v[92:95], v[132:135], v[212:215], v[92:95]
	v_mfma_f32_16x16x32_bf16 v[88:91], v[140:143], v[212:215], v[88:91]
	v_mfma_f32_16x16x32_bf16 v[76:79], v[132:135], v[220:223], v[76:79]
	v_mfma_f32_16x16x32_bf16 v[72:75], v[140:143], v[220:223], v[72:75]
	v_mfma_f32_16x16x32_bf16 v[116:119], v[144:147], v[168:171], v[116:119]
	v_mfma_f32_16x16x32_bf16 v[112:115], v[152:155], v[168:171], v[112:115]
	v_mfma_f32_16x16x32_bf16 v[100:103], v[144:147], v[200:203], v[100:103]
	v_mfma_f32_16x16x32_bf16 v[96:99], v[152:155], v[200:203], v[96:99]
	v_mfma_f32_16x16x32_bf16 v[84:87], v[144:147], v[208:211], v[84:87]
	v_mfma_f32_16x16x32_bf16 v[80:83], v[152:155], v[208:211], v[80:83]
	v_mfma_f32_16x16x32_bf16 v[68:71], v[144:147], v[216:219], v[68:71]
	v_mfma_f32_16x16x32_bf16 v[64:67], v[152:155], v[216:219], v[64:67]
	v_mfma_f32_16x16x32_bf16 v[116:119], v[148:151], v[196:199], v[116:119]
	v_mfma_f32_16x16x32_bf16 v[112:115], v[164:167], v[196:199], v[112:115]
	v_mfma_f32_16x16x32_bf16 v[100:103], v[148:151], v[204:207], v[100:103]
	v_mfma_f32_16x16x32_bf16 v[96:99], v[164:167], v[204:207], v[96:99]
	v_mfma_f32_16x16x32_bf16 v[84:87], v[148:151], v[212:215], v[84:87]
	v_mfma_f32_16x16x32_bf16 v[80:83], v[164:167], v[212:215], v[80:83]
	v_mfma_f32_16x16x32_bf16 v[68:71], v[148:151], v[220:223], v[68:71]
	v_mfma_f32_16x16x32_bf16 v[64:67], v[164:167], v[220:223], v[64:67]
	s_barrier
	s_mov_b32 m0, s97
	v_lshl_add_u64 v[192:193], s[6:7], 0, v[160:161]
	ds_read_b128 v[168:171], v191 offset:16384
	ds_read_b128 v[196:199], v191 offset:17408
	ds_read_b128 v[200:203], v191 offset:18432
	ds_read_b128 v[204:207], v191 offset:19456
	ds_read_b128 v[208:211], v191 offset:20480
	ds_read_b128 v[212:215], v191 offset:21504
	ds_read_b128 v[216:219], v191 offset:22528
	ds_read_b128 v[220:223], v191 offset:23552
	global_load_lds_dwordx4 v[192:193], off
	v_lshl_add_u64 v[224:225], s[6:7], 0, v[162:163]
	s_mov_b32 m0, s88
	v_lshl_add_u64 v[226:227], s[14:15], 0, v[160:161]
	global_load_lds_dwordx4 v[224:225], off
	s_mov_b32 m0, s89
	v_lshl_add_u64 v[228:229], vcc, 0, v[158:159]
	global_load_lds_dwordx4 v[226:227], off
	v_lshl_add_u64 v[226:227], s[14:15], 0, v[162:163]
	s_mov_b32 m0, s96
	s_nop 0
	global_load_lds_dwordx4 v[226:227], off
	v_lshl_add_u64 v[226:227], vcc, 0, v[156:157]
	s_mov_b32 m0, s25
	s_nop 0
	global_load_lds_dwordx4 v[226:227], off
	s_mov_b32 m0, s49
	s_nop 0
	global_load_lds_dwordx4 v[228:229], off
	s_waitcnt vmcnt(8)
	s_waitcnt lgkmcnt(0)
	s_barrier
	s_waitcnt lgkmcnt(0)
	v_mfma_f32_16x16x32_bf16 v[60:63], v[128:131], v[168:171], v[60:63]
	v_mfma_f32_16x16x32_bf16 v[56:59], v[136:139], v[168:171], v[56:59]
	v_mfma_f32_16x16x32_bf16 v[44:47], v[128:131], v[200:203], v[44:47]
	v_mfma_f32_16x16x32_bf16 v[40:43], v[136:139], v[200:203], v[40:43]
	v_mfma_f32_16x16x32_bf16 v[28:31], v[128:131], v[208:211], v[28:31]
	v_mfma_f32_16x16x32_bf16 v[24:27], v[136:139], v[208:211], v[24:27]
	v_mfma_f32_16x16x32_bf16 v[12:15], v[128:131], v[216:219], v[12:15]
	v_mfma_f32_16x16x32_bf16 v[8:11], v[136:139], v[216:219], v[8:11]
	v_mfma_f32_16x16x32_bf16 v[60:63], v[132:135], v[196:199], v[60:63]
	v_mfma_f32_16x16x32_bf16 v[56:59], v[140:143], v[196:199], v[56:59]
	v_mfma_f32_16x16x32_bf16 v[44:47], v[132:135], v[204:207], v[44:47]
	v_mfma_f32_16x16x32_bf16 v[40:43], v[140:143], v[204:207], v[40:43]
	v_mfma_f32_16x16x32_bf16 v[28:31], v[132:135], v[212:215], v[28:31]
	v_mfma_f32_16x16x32_bf16 v[24:27], v[140:143], v[212:215], v[24:27]
	v_mfma_f32_16x16x32_bf16 v[12:15], v[132:135], v[220:223], v[12:15]
	v_mfma_f32_16x16x32_bf16 v[8:11], v[140:143], v[220:223], v[8:11]
	v_mfma_f32_16x16x32_bf16 v[52:55], v[144:147], v[168:171], v[52:55]
	v_mfma_f32_16x16x32_bf16 v[48:51], v[152:155], v[168:171], v[48:51]
	v_mfma_f32_16x16x32_bf16 v[36:39], v[144:147], v[200:203], v[36:39]
	v_mfma_f32_16x16x32_bf16 v[32:35], v[152:155], v[200:203], v[32:35]
	v_mfma_f32_16x16x32_bf16 v[20:23], v[144:147], v[208:211], v[20:23]
	v_mfma_f32_16x16x32_bf16 v[16:19], v[152:155], v[208:211], v[16:19]
	v_mfma_f32_16x16x32_bf16 v[4:7], v[144:147], v[216:219], v[4:7]
	v_mfma_f32_16x16x32_bf16 v[0:3], v[152:155], v[216:219], v[0:3]
	v_mfma_f32_16x16x32_bf16 v[52:55], v[148:151], v[196:199], v[52:55]
	v_mfma_f32_16x16x32_bf16 v[48:51], v[164:167], v[196:199], v[48:51]
	v_mfma_f32_16x16x32_bf16 v[36:39], v[148:151], v[204:207], v[36:39]
	v_mfma_f32_16x16x32_bf16 v[32:35], v[164:167], v[204:207], v[32:35]
	v_mfma_f32_16x16x32_bf16 v[20:23], v[148:151], v[212:215], v[20:23]
	v_mfma_f32_16x16x32_bf16 v[16:19], v[164:167], v[212:215], v[16:19]
	v_mfma_f32_16x16x32_bf16 v[4:7], v[148:151], v[220:223], v[4:7]
	v_mfma_f32_16x16x32_bf16 v[0:3], v[164:167], v[220:223], v[0:3]
	s_barrier
; #define PG8_STAGE(bufoff, gbase, voff) do { _Pragma("unroll") for (int _i = 0; _i < 2; ++_i) \
;         __builtin_amdgcn_global_load_lds((const unsigned*)((const char*)(gbase) + (voff)[_i]), (LAS unsigned*)(lds + (bufoff) + ldsw + _i * 8192), 16, 0, 0); } while (0)
; #define PG8_LDA(dst, b, h) do { _Pragma("unroll") for (int m = 0; m < 4; ++m) _Pragma("unroll") for (int k = 0; k < 2; ++k) dst[m][k] = *(const LAS bf16x8*)(lds + PG8_SA(b, h) + aoff + m * 2048 + k * 1024); } while (0)
; #define PG8_LDB(dst, b, h) do { _Pragma("unroll") for (int n = 0; n < 2; ++n) _Pragma("unroll") for (int k = 0; k < 2; ++k) dst[n][k] = *(const LAS bf16x8*)(lds + PG8_SB(b, h) + boff + n * 2048 + k * 1024); } while (0)
; #define PG8_MMA(ai, bj, At, Bt) do { __builtin_amdgcn_s_setprio(1); _Pragma("unroll") for (int m = 0; m < 4; ++m) _Pragma("unroll") for (int n = 0; n < 2; ++n) _Pragma("unroll") for (int k = 0; k < 2; ++k) \
;         acc[ai][bj][m][n] = __builtin_amdgcn_mfma_f32_16x16x32_bf16(Bt[n][k], At[m][k], acc[ai][bj][m][n], 0, 0, 0); __builtin_amdgcn_s_setprio(0); } while (0)
; #define PG8_WAIT_V(n) asm volatile("s_waitcnt vmcnt(" #n ")" ::: "memory")
; #define PG8_WAIT_L(n) asm volatile("s_waitcnt lgkmcnt(" #n ")" ::: "memory")
; #define PG8_BAR __builtin_amdgcn_s_barrier()
; #define PG8_SCHED __builtin_amdgcn_sched_barrier(0)
; template <class Epi, class Sched>
; __device__ __forceinline__ void gemm_phase(LAS unsigned char* lds, const Gemm g, const Sched& S, const Epi& E) {
;     ...
;             PG8_LDB(B0, 1, 0); PG8_LDB(B1, 1, 1); PG8_SCHED; PG8_LDA(At, 1, 0); PG8_STAGE(PG8_SA(0, 1), a2 + hstepA, voffA);
;             PG8_WAIT_V(8); PG8_WAIT_L(0); PG8_BAR; PG8_MMA(0, 0, At, B0); PG8_MMA(0, 1, At, B1); PG8_BAR; PG8_SCHED;
;             PG8_LDA(At, 1, 1); PG8_STAGE(PG8_SB(1, 0), b3, voffB); PG8_STAGE(PG8_SB(1, 1), b3 + hstepB, voffB); PG8_STAGE(PG8_SA(1, 0), a3, voffA);
;             PG8_WAIT_V(8); PG8_WAIT_L(0); PG8_BAR; PG8_MMA(1, 0, At, B0); PG8_MMA(1, 1, At, B1); PG8_BAR; PG8_SCHED;
;         }
;         if (wr == 0) PG8_BAR;
	v_add_u32_e32 v140, s35, v174
	v_add_u32_e32 v164, s0, v174
	ds_read_b128 v[128:131], v140
	ds_read_b128 v[132:135], v140 offset:1024
	ds_read_b128 v[136:139], v140 offset:2048
	ds_read_b128 v[140:143], v140 offset:3072
	ds_read_b128 v[144:147], v164
	ds_read_b128 v[148:151], v164 offset:1024
	ds_read_b128 v[152:155], v164 offset:2048
	ds_read_b128 v[164:167], v164 offset:3072
	s_mov_b32 m0, s82
	v_lshl_add_u64 v[230:231], s[68:69], 0, v[156:157]
	ds_read_b128 v[168:171], v191 offset:32768
	ds_read_b128 v[196:199], v191 offset:33792
	ds_read_b128 v[200:203], v191 offset:34816
	ds_read_b128 v[204:207], v191 offset:35840
	ds_read_b128 v[208:211], v191 offset:36864
	ds_read_b128 v[212:215], v191 offset:37888
	ds_read_b128 v[216:219], v191 offset:38912
	ds_read_b128 v[220:223], v191 offset:39936
	global_load_lds_dwordx4 v[230:231], off
	v_lshl_add_u64 v[230:231], s[68:69], 0, v[158:159]
	s_mov_b32 m0, s33
	s_nop 0
	global_load_lds_dwordx4 v[230:231], off
	s_waitcnt vmcnt(8)
	s_waitcnt lgkmcnt(0)
	s_barrier
	s_waitcnt lgkmcnt(0)
	v_mfma_f32_16x16x32_bf16 v[124:127], v[128:131], v[168:171], v[124:127]
	v_mfma_f32_16x16x32_bf16 v[120:123], v[136:139], v[168:171], v[120:123]
	v_mfma_f32_16x16x32_bf16 v[108:111], v[128:131], v[200:203], v[108:111]
	v_mfma_f32_16x16x32_bf16 v[104:107], v[136:139], v[200:203], v[104:107]
	v_mfma_f32_16x16x32_bf16 v[92:95], v[128:131], v[208:211], v[92:95]
	v_mfma_f32_16x16x32_bf16 v[88:91], v[136:139], v[208:211], v[88:91]
	v_mfma_f32_16x16x32_bf16 v[76:79], v[128:131], v[216:219], v[76:79]
	v_mfma_f32_16x16x32_bf16 v[72:75], v[136:139], v[216:219], v[72:75]
	v_mfma_f32_16x16x32_bf16 v[124:127], v[132:135], v[196:199], v[124:127]
	v_mfma_f32_16x16x32_bf16 v[120:123], v[140:143], v[196:199], v[120:123]
	v_mfma_f32_16x16x32_bf16 v[108:111], v[132:135], v[204:207], v[108:111]
	v_mfma_f32_16x16x32_bf16 v[104:107], v[140:143], v[204:207], v[104:107]
	v_mfma_f32_16x16x32_bf16 v[92:95], v[132:135], v[212:215], v[92:95]
	v_mfma_f32_16x16x32_bf16 v[88:91], v[140:143], v[212:215], v[88:91]
	v_mfma_f32_16x16x32_bf16 v[76:79], v[132:135], v[220:223], v[76:79]
	v_mfma_f32_16x16x32_bf16 v[72:75], v[140:143], v[220:223], v[72:75]
	v_mfma_f32_16x16x32_bf16 v[116:119], v[144:147], v[168:171], v[116:119]
	v_mfma_f32_16x16x32_bf16 v[112:115], v[152:155], v[168:171], v[112:115]
	v_mfma_f32_16x16x32_bf16 v[100:103], v[144:147], v[200:203], v[100:103]
	v_mfma_f32_16x16x32_bf16 v[96:99], v[152:155], v[200:203], v[96:99]
	v_mfma_f32_16x16x32_bf16 v[84:87], v[144:147], v[208:211], v[84:87]
	v_mfma_f32_16x16x32_bf16 v[80:83], v[152:155], v[208:211], v[80:83]
	v_mfma_f32_16x16x32_bf16 v[68:71], v[144:147], v[216:219], v[68:71]
	v_mfma_f32_16x16x32_bf16 v[64:67], v[152:155], v[216:219], v[64:67]
	v_mfma_f32_16x16x32_bf16 v[116:119], v[148:151], v[196:199], v[116:119]
	v_mfma_f32_16x16x32_bf16 v[112:115], v[164:167], v[196:199], v[112:115]
	v_mfma_f32_16x16x32_bf16 v[100:103], v[148:151], v[204:207], v[100:103]
	v_mfma_f32_16x16x32_bf16 v[96:99], v[164:167], v[204:207], v[96:99]
	v_mfma_f32_16x16x32_bf16 v[84:87], v[148:151], v[212:215], v[84:87]
	v_mfma_f32_16x16x32_bf16 v[80:83], v[164:167], v[212:215], v[80:83]
	v_mfma_f32_16x16x32_bf16 v[68:71], v[148:151], v[220:223], v[68:71]
	v_mfma_f32_16x16x32_bf16 v[64:67], v[164:167], v[220:223], v[64:67]
	s_barrier
	s_mov_b32 m0, s23
	v_lshl_add_u64 v[192:193], v[192:193], 0, s[30:31]
	ds_read_b128 v[168:171], v191 offset:49152
	ds_read_b128 v[196:199], v191 offset:50176
	ds_read_b128 v[200:203], v191 offset:51200
	ds_read_b128 v[204:207], v191 offset:52224
	ds_read_b128 v[208:211], v191 offset:53248
	ds_read_b128 v[212:215], v191 offset:54272
	ds_read_b128 v[216:219], v191 offset:55296
	ds_read_b128 v[220:223], v191 offset:56320
	global_load_lds_dwordx4 v[192:193], off
	v_lshl_add_u64 v[192:193], v[224:225], 0, s[30:31]
	s_mov_b32 m0, s26
	s_nop 0
	global_load_lds_dwordx4 v[192:193], off
	v_lshl_add_u64 v[192:193], s[56:57], 0, v[160:161]
	s_mov_b32 m0, s83
	s_nop 0
	global_load_lds_dwordx4 v[192:193], off
	v_lshl_add_u64 v[192:193], s[56:57], 0, v[162:163]
	s_mov_b32 m0, s80
	s_nop 0
	global_load_lds_dwordx4 v[192:193], off
	v_lshl_add_u64 v[192:193], v[226:227], 0, s[30:31]
	s_mov_b32 m0, s90
	s_nop 0
	global_load_lds_dwordx4 v[192:193], off
	v_lshl_add_u64 v[192:193], v[228:229], 0, s[30:31]
	s_mov_b32 m0, s21
	s_nop 0
	global_load_lds_dwordx4 v[192:193], off
	s_waitcnt vmcnt(8)
	s_waitcnt lgkmcnt(0)
	s_barrier
	s_waitcnt lgkmcnt(0)
	v_mfma_f32_16x16x32_bf16 v[60:63], v[128:131], v[168:171], v[60:63]
	v_mfma_f32_16x16x32_bf16 v[56:59], v[136:139], v[168:171], v[56:59]
	v_mfma_f32_16x16x32_bf16 v[44:47], v[128:131], v[200:203], v[44:47]
	v_mfma_f32_16x16x32_bf16 v[40:43], v[136:139], v[200:203], v[40:43]
	v_mfma_f32_16x16x32_bf16 v[28:31], v[128:131], v[208:211], v[28:31]
	v_mfma_f32_16x16x32_bf16 v[24:27], v[136:139], v[208:211], v[24:27]
	v_mfma_f32_16x16x32_bf16 v[12:15], v[128:131], v[216:219], v[12:15]
	v_mfma_f32_16x16x32_bf16 v[8:11], v[136:139], v[216:219], v[8:11]
	v_mfma_f32_16x16x32_bf16 v[60:63], v[132:135], v[196:199], v[60:63]
	v_mfma_f32_16x16x32_bf16 v[56:59], v[140:143], v[196:199], v[56:59]
	v_mfma_f32_16x16x32_bf16 v[44:47], v[132:135], v[204:207], v[44:47]
	v_mfma_f32_16x16x32_bf16 v[40:43], v[140:143], v[204:207], v[40:43]
	v_mfma_f32_16x16x32_bf16 v[28:31], v[132:135], v[212:215], v[28:31]
	v_mfma_f32_16x16x32_bf16 v[24:27], v[140:143], v[212:215], v[24:27]
	v_mfma_f32_16x16x32_bf16 v[12:15], v[132:135], v[220:223], v[12:15]
	v_mfma_f32_16x16x32_bf16 v[8:11], v[140:143], v[220:223], v[8:11]
	v_mfma_f32_16x16x32_bf16 v[52:55], v[144:147], v[168:171], v[52:55]
	v_mfma_f32_16x16x32_bf16 v[48:51], v[152:155], v[168:171], v[48:51]
	v_mfma_f32_16x16x32_bf16 v[36:39], v[144:147], v[200:203], v[36:39]
	v_mfma_f32_16x16x32_bf16 v[32:35], v[152:155], v[200:203], v[32:35]
	v_mfma_f32_16x16x32_bf16 v[20:23], v[144:147], v[208:211], v[20:23]
	v_mfma_f32_16x16x32_bf16 v[16:19], v[152:155], v[208:211], v[16:19]
	v_mfma_f32_16x16x32_bf16 v[4:7], v[144:147], v[216:219], v[4:7]
	v_mfma_f32_16x16x32_bf16 v[0:3], v[152:155], v[216:219], v[0:3]
	v_mfma_f32_16x16x32_bf16 v[52:55], v[148:151], v[196:199], v[52:55]
	v_mfma_f32_16x16x32_bf16 v[48:51], v[164:167], v[196:199], v[48:51]
	v_mfma_f32_16x16x32_bf16 v[36:39], v[148:151], v[204:207], v[36:39]
	v_mfma_f32_16x16x32_bf16 v[32:35], v[164:167], v[204:207], v[32:35]
	v_mfma_f32_16x16x32_bf16 v[20:23], v[148:151], v[212:215], v[20:23]
	v_mfma_f32_16x16x32_bf16 v[16:19], v[164:167], v[212:215], v[16:19]
	v_mfma_f32_16x16x32_bf16 v[4:7], v[148:151], v[220:223], v[4:7]
	v_mfma_f32_16x16x32_bf16 v[0:3], v[164:167], v[220:223], v[0:3]
	s_barrier
	s_movk_i32 s6, 0x100
	s_andn2_b64 vcc, exec, s[54:55]
	s_mov_b64 s[56:57], -1
	s_mov_b64 s[54:55], 0
	s_cbranch_vccz .LBB0_628
	s_setprio 0
	s_and_b64 vcc, exec, s[18:19]
	s_cbranch_vccz .LBB0_631
	s_barrier

; #define PG8_STAGE(bufoff, gbase, voff) do { _Pragma("unroll") for (int _i = 0; _i < 2; ++_i) \
;         __builtin_amdgcn_global_load_lds((const unsigned*)((const char*)(gbase) + (voff)[_i]), (LAS unsigned*)(lds + (bufoff) + ldsw + _i * 8192), 16, 0, 0); } while (0)
; #define PG8_LDA(dst, b, h) do { _Pragma("unroll") for (int m = 0; m < 4; ++m) _Pragma("unroll") for (int k = 0; k < 2; ++k) dst[m][k] = *(const LAS bf16x8*)(lds + PG8_SA(b, h) + aoff + m * 2048 + k * 1024); } while (0)
; #define PG8_LDB(dst, b, h) do { _Pragma("unroll") for (int n = 0; n < 2; ++n) _Pragma("unroll") for (int k = 0; k < 2; ++k) dst[n][k] = *(const LAS bf16x8*)(lds + PG8_SB(b, h) + boff + n * 2048 + k * 1024); } while (0)
; #define PG8_WAIT_V(n) asm volatile("s_waitcnt vmcnt(" #n ")" ::: "memory")
; #define PG8_WAIT_L(n) asm volatile("s_waitcnt lgkmcnt(" #n ")" ::: "memory")
; #define PG8_BAR __builtin_amdgcn_s_barrier()
; #define PG8_SCHED __builtin_amdgcn_sched_barrier(0)
; template <class Epi, class Sched>
; __device__ __forceinline__ void gemm_phase(LAS unsigned char* lds, const Gemm g, const Sched& S, const Epi& E) {
;     ...
;         const bool has_next = S.next(ui + 1, nxt);
;         const char* nA = has_next ? (const char*)g.A + (size_t)nxt.pm * tstepA + (size_t)nxt.pn * apn : cA; const char* nB = has_next ? (const char*)g.Bt + (size_t)nxt.pn * tstepB : cB;
;         for (int t = 0; t < nt; t += 2) {
;             const bool last = (t == nt - 2);
;             const char* a1 = cA + (size_t)(t + 1) * kstep;
;             const char* a2 = last ? nA : cA + (size_t)(t + 2) * kstep; const char* b2 = last ? nB : cB + (size_t)(t + 2) * kstep;
;             const char* a3 = a2 + kstep; const char* b3 = b2 + kstep;
;             PG8_LDB(B0, 0, 0); PG8_LDB(B1, 0, 1); PG8_SCHED; PG8_LDA(At, 0, 0); PG8_STAGE(PG8_SA(1, 1), a1 + hstepA, voffA);
;             PG8_WAIT_V(8); PG8_WAIT_L(0); PG8_BAR; PG8_MMA(0, 0, At, B0); PG8_MMA(0, 1, At, B1); PG8_BAR; PG8_SCHED;
;             PG8_LDA(At, 0, 1); PG8_STAGE(PG8_SB(0, 0), b2, voffB); PG8_STAGE(PG8_SB(0, 1), b2 + hstepB, voffB); PG8_STAGE(PG8_SA(0, 0), a2, voffA);
;             PG8_WAIT_V(8); PG8_WAIT_L(0); PG8_BAR; PG8_MMA(1, 0, At, B0); PG8_MMA(1, 1, At, B1); PG8_BAR; PG8_SCHED;
;             PG8_LDB(B0, 1, 0); PG8_LDB(B1, 1, 1); PG8_SCHED; PG8_LDA(At, 1, 0); PG8_STAGE(PG8_SA(0, 1), a2 + hstepA, voffA);
.LBB0_806:
	s_add_u32 s33, s46, 0x100
	s_addc_u32 s53, s47, 0
	s_mov_b32 s54, -2
	s_waitcnt lgkmcnt(0)
	s_cmp_eq_u64 s[18:19], 0
	s_cbranch_scc0 .Lprio_807
	s_setprio 1
.Lprio_807:
	s_add_u32 s46, s44, 0x100
	s_addc_u32 s47, s45, 0
	s_add_i32 s0, 0, 0x10000
	s_cmp_eq_u32 s54, 40
	s_cselect_b32 s15, s23, s47
	s_cselect_b32 s14, s22, s46
	s_cselect_b32 s7, s35, s53
	s_cselect_b32 s6, s34, s33
	s_add_i32 s26, 0, 0x14000
	v_add_u32_e32 v140, s0, v186
	v_add_u32_e32 v168, s26, v186
	ds_read_b128 v[128:131], v140
	ds_read_b128 v[132:135], v140 offset:1024
	ds_read_b128 v[136:139], v140 offset:2048
	ds_read_b128 v[140:143], v140 offset:3072
	ds_read_b128 v[144:147], v168
	ds_read_b128 v[148:151], v168 offset:1024
	ds_read_b128 v[152:155], v168 offset:2048
	ds_read_b128 v[168:171], v168 offset:3072
	v_lshl_add_u64 v[226:227], s[44:45], 0, v[164:165]
	s_add_i32 m0, s49, 0xc000
	ds_read_b128 v[172:175], v196
	ds_read_b128 v[198:201], v196 offset:1024
	ds_read_b128 v[202:205], v196 offset:2048
	ds_read_b128 v[206:209], v196 offset:3072
	ds_read_b128 v[210:213], v196 offset:4096
	ds_read_b128 v[214:217], v196 offset:5120
	ds_read_b128 v[218:221], v196 offset:6144
	ds_read_b128 v[222:225], v196 offset:7168
	global_load_lds_dwordx4 v[226:227], off
	v_lshl_add_u64 v[226:227], s[44:45], 0, v[166:167]
	s_add_i32 m0, s49, 0xe000
	s_nop 0
	global_load_lds_dwordx4 v[226:227], off
	s_waitcnt vmcnt(8)
	s_waitcnt lgkmcnt(0)
	s_barrier
	s_waitcnt lgkmcnt(0)
	v_mfma_f32_16x16x32_bf16 v[124:127], v[128:131], v[172:175], 0
	v_mfma_f32_16x16x32_bf16 v[120:123], v[136:139], v[172:175], 0
	v_mfma_f32_16x16x32_bf16 v[108:111], v[128:131], v[202:205], 0
	v_mfma_f32_16x16x32_bf16 v[104:107], v[136:139], v[202:205], 0
	v_mfma_f32_16x16x32_bf16 v[92:95], v[128:131], v[210:213], 0
	v_mfma_f32_16x16x32_bf16 v[88:91], v[136:139], v[210:213], 0
	v_mfma_f32_16x16x32_bf16 v[76:79], v[128:131], v[218:221], 0
	v_mfma_f32_16x16x32_bf16 v[72:75], v[136:139], v[218:221], 0
	v_mfma_f32_16x16x32_bf16 v[124:127], v[132:135], v[198:201], v[124:127]
	v_mfma_f32_16x16x32_bf16 v[120:123], v[140:143], v[198:201], v[120:123]
	v_mfma_f32_16x16x32_bf16 v[108:111], v[132:135], v[206:209], v[108:111]
	v_mfma_f32_16x16x32_bf16 v[104:107], v[140:143], v[206:209], v[104:107]
	v_mfma_f32_16x16x32_bf16 v[92:95], v[132:135], v[214:217], v[92:95]
	v_mfma_f32_16x16x32_bf16 v[88:91], v[140:143], v[214:217], v[88:91]
	v_mfma_f32_16x16x32_bf16 v[76:79], v[132:135], v[222:225], v[76:79]
	v_mfma_f32_16x16x32_bf16 v[72:75], v[140:143], v[222:225], v[72:75]
	v_mfma_f32_16x16x32_bf16 v[116:119], v[144:147], v[172:175], 0
	v_mfma_f32_16x16x32_bf16 v[112:115], v[152:155], v[172:175], 0
	v_mfma_f32_16x16x32_bf16 v[100:103], v[144:147], v[202:205], 0
	v_mfma_f32_16x16x32_bf16 v[96:99], v[152:155], v[202:205], 0
	v_mfma_f32_16x16x32_bf16 v[84:87], v[144:147], v[210:213], 0
	v_mfma_f32_16x16x32_bf16 v[80:83], v[152:155], v[210:213], 0
	v_mfma_f32_16x16x32_bf16 v[68:71], v[144:147], v[218:221], 0
	v_mfma_f32_16x16x32_bf16 v[64:67], v[152:155], v[218:221], 0
	v_mfma_f32_16x16x32_bf16 v[116:119], v[148:151], v[198:201], v[116:119]
	v_mfma_f32_16x16x32_bf16 v[112:115], v[168:171], v[198:201], v[112:115]
	v_mfma_f32_16x16x32_bf16 v[100:103], v[148:151], v[206:209], v[100:103]
	v_mfma_f32_16x16x32_bf16 v[96:99], v[168:171], v[206:209], v[96:99]
	v_mfma_f32_16x16x32_bf16 v[84:87], v[148:151], v[214:217], v[84:87]
	v_mfma_f32_16x16x32_bf16 v[80:83], v[168:171], v[214:217], v[80:83]
	v_mfma_f32_16x16x32_bf16 v[68:71], v[148:151], v[222:225], v[68:71]
	v_mfma_f32_16x16x32_bf16 v[64:67], v[168:171], v[222:225], v[64:67]
	s_barrier
	s_add_i32 s0, s0, s20
	v_lshl_add_u64 v[226:227], s[6:7], 0, v[160:161]
	s_mov_b32 m0, s0
	ds_read_b128 v[172:175], v196 offset:16384
	ds_read_b128 v[198:201], v196 offset:17408
	ds_read_b128 v[202:205], v196 offset:18432
	ds_read_b128 v[206:209], v196 offset:19456
	ds_read_b128 v[210:213], v196 offset:20480
	ds_read_b128 v[214:217], v196 offset:21504
	ds_read_b128 v[218:221], v196 offset:22528
	ds_read_b128 v[222:225], v196 offset:23552
	global_load_lds_dwordx4 v[226:227], off
	s_add_i32 m0, s0, 0x2000
	s_add_u32 s44, s6, 0xb0000
	v_lshl_add_u64 v[228:229], s[6:7], 0, v[162:163]
	s_addc_u32 s45, s7, 0
	s_add_i32 s0, s26, s20
	global_load_lds_dwordx4 v[228:229], off
	v_lshl_add_u64 v[230:231], s[44:45], 0, v[160:161]
	s_mov_b32 m0, s0
	v_lshl_add_u64 v[232:233], s[14:15], 0, v[158:159]
	global_load_lds_dwordx4 v[230:231], off
	v_lshl_add_u64 v[230:231], s[44:45], 0, v[162:163]
	s_add_i32 m0, s0, 0x2000
	s_nop 0
	global_load_lds_dwordx4 v[230:231], off
	v_lshl_add_u64 v[230:231], s[14:15], 0, v[156:157]
	s_mov_b32 m0, s49
	s_nop 0
	global_load_lds_dwordx4 v[230:231], off
	s_mov_b32 m0, s50
	s_nop 0
	global_load_lds_dwordx4 v[232:233], off
	s_waitcnt vmcnt(8)
	s_waitcnt lgkmcnt(0)
	s_barrier
; #define PG8_STAGE(bufoff, gbase, voff) do { _Pragma("unroll") for (int _i = 0; _i < 2; ++_i) \
;         __builtin_amdgcn_global_load_lds((const unsigned*)((const char*)(gbase) + (voff)[_i]), (LAS unsigned*)(lds + (bufoff) + ldsw + _i * 8192), 16, 0, 0); } while (0)
; #define PG8_LDA(dst, b, h) do { _Pragma("unroll") for (int m = 0; m < 4; ++m) _Pragma("unroll") for (int k = 0; k < 2; ++k) dst[m][k] = *(const LAS bf16x8*)(lds + PG8_SA(b, h) + aoff + m * 2048 + k * 1024); } while (0)
; #define PG8_LDB(dst, b, h) do { _Pragma("unroll") for (int n = 0; n < 2; ++n) _Pragma("unroll") for (int k = 0; k < 2; ++k) dst[n][k] = *(const LAS bf16x8*)(lds + PG8_SB(b, h) + boff + n * 2048 + k * 1024); } while (0)
; #define PG8_MMA(ai, bj, At, Bt) do { __builtin_amdgcn_s_setprio(1); _Pragma("unroll") for (int m = 0; m < 4; ++m) _Pragma("unroll") for (int n = 0; n < 2; ++n) _Pragma("unroll") for (int k = 0; k < 2; ++k) \
;         acc[ai][bj][m][n] = __builtin_amdgcn_mfma_f32_16x16x32_bf16(Bt[n][k], At[m][k], acc[ai][bj][m][n], 0, 0, 0); __builtin_amdgcn_s_setprio(0); } while (0)
; #define PG8_WAIT_V(n) asm volatile("s_waitcnt vmcnt(" #n ")" ::: "memory")
; #define PG8_WAIT_L(n) asm volatile("s_waitcnt lgkmcnt(" #n ")" ::: "memory")
; #define PG8_BAR __builtin_amdgcn_s_barrier()
; #define PG8_SCHED __builtin_amdgcn_sched_barrier(0)
; template <class Epi, class Sched>
; __device__ __forceinline__ void gemm_phase(LAS unsigned char* lds, const Gemm g, const Sched& S, const Epi& E) {
;     ...
;             PG8_WAIT_V(8); PG8_WAIT_L(0); PG8_BAR; PG8_MMA(1, 0, At, B0); PG8_MMA(1, 1, At, B1); PG8_BAR; PG8_SCHED;
;             PG8_LDB(B0, 1, 0); PG8_LDB(B1, 1, 1); PG8_SCHED; PG8_LDA(At, 1, 0); PG8_STAGE(PG8_SA(0, 1), a2 + hstepA, voffA);
;             PG8_WAIT_V(8); PG8_WAIT_L(0); PG8_BAR; PG8_MMA(0, 0, At, B0); PG8_MMA(0, 1, At, B1); PG8_BAR; PG8_SCHED;
;             PG8_LDA(At, 1, 1); PG8_STAGE(PG8_SB(1, 0), b3, voffB); PG8_STAGE(PG8_SB(1, 1), b3 + hstepB, voffB); PG8_STAGE(PG8_SA(1, 0), a3, voffA);
	s_waitcnt lgkmcnt(0)
	v_mfma_f32_16x16x32_bf16 v[60:63], v[128:131], v[172:175], 0
	v_mfma_f32_16x16x32_bf16 v[56:59], v[136:139], v[172:175], 0
	v_mfma_f32_16x16x32_bf16 v[44:47], v[128:131], v[202:205], 0
	v_mfma_f32_16x16x32_bf16 v[40:43], v[136:139], v[202:205], 0
	v_mfma_f32_16x16x32_bf16 v[28:31], v[128:131], v[210:213], 0
	v_mfma_f32_16x16x32_bf16 v[24:27], v[136:139], v[210:213], 0
	v_mfma_f32_16x16x32_bf16 v[12:15], v[128:131], v[218:221], 0
	v_mfma_f32_16x16x32_bf16 v[8:11], v[136:139], v[218:221], 0
	v_mfma_f32_16x16x32_bf16 v[60:63], v[132:135], v[198:201], v[60:63]
	v_mfma_f32_16x16x32_bf16 v[56:59], v[140:143], v[198:201], v[56:59]
	v_mfma_f32_16x16x32_bf16 v[44:47], v[132:135], v[206:209], v[44:47]
	v_mfma_f32_16x16x32_bf16 v[40:43], v[140:143], v[206:209], v[40:43]
	v_mfma_f32_16x16x32_bf16 v[28:31], v[132:135], v[214:217], v[28:31]
	v_mfma_f32_16x16x32_bf16 v[24:27], v[140:143], v[214:217], v[24:27]
	v_mfma_f32_16x16x32_bf16 v[12:15], v[132:135], v[222:225], v[12:15]
	v_mfma_f32_16x16x32_bf16 v[8:11], v[140:143], v[222:225], v[8:11]
	v_mfma_f32_16x16x32_bf16 v[52:55], v[144:147], v[172:175], 0
	v_mfma_f32_16x16x32_bf16 v[48:51], v[152:155], v[172:175], 0
	v_mfma_f32_16x16x32_bf16 v[36:39], v[144:147], v[202:205], 0
	v_mfma_f32_16x16x32_bf16 v[32:35], v[152:155], v[202:205], 0
	v_mfma_f32_16x16x32_bf16 v[20:23], v[144:147], v[210:213], 0
	v_mfma_f32_16x16x32_bf16 v[16:19], v[152:155], v[210:213], 0
	v_mfma_f32_16x16x32_bf16 v[4:7], v[144:147], v[218:221], 0
	v_mfma_f32_16x16x32_bf16 v[0:3], v[152:155], v[218:221], 0
	v_mfma_f32_16x16x32_bf16 v[52:55], v[148:151], v[198:201], v[52:55]
	v_mfma_f32_16x16x32_bf16 v[48:51], v[168:171], v[198:201], v[48:51]
	v_mfma_f32_16x16x32_bf16 v[36:39], v[148:151], v[206:209], v[36:39]
	v_mfma_f32_16x16x32_bf16 v[32:35], v[168:171], v[206:209], v[32:35]
	v_mfma_f32_16x16x32_bf16 v[20:23], v[148:151], v[214:217], v[20:23]
	v_mfma_f32_16x16x32_bf16 v[16:19], v[168:171], v[214:217], v[16:19]
	v_mfma_f32_16x16x32_bf16 v[4:7], v[148:151], v[222:225], v[4:7]
	v_mfma_f32_16x16x32_bf16 v[0:3], v[168:171], v[222:225], v[0:3]
	s_barrier
	s_add_i32 s0, 0, 0x18000
	s_add_i32 s26, 0, 0x1c000
	v_add_u32_e32 v140, s0, v186
	v_add_u32_e32 v168, s26, v186
	ds_read_b128 v[128:131], v140
	ds_read_b128 v[132:135], v140 offset:1024
	ds_read_b128 v[136:139], v140 offset:2048
	ds_read_b128 v[140:143], v140 offset:3072
	ds_read_b128 v[144:147], v168
	ds_read_b128 v[148:151], v168 offset:1024
	ds_read_b128 v[152:155], v168 offset:2048
	ds_read_b128 v[168:171], v168 offset:3072
	s_add_u32 s14, s14, 0xb0000
	s_addc_u32 s15, s15, 0
	s_mov_b32 m0, s51
	v_lshl_add_u64 v[234:235], s[14:15], 0, v[156:157]
	ds_read_b128 v[172:175], v196 offset:32768
	ds_read_b128 v[198:201], v196 offset:33792
	ds_read_b128 v[202:205], v196 offset:34816
	ds_read_b128 v[206:209], v196 offset:35840
	ds_read_b128 v[210:213], v196 offset:36864
	ds_read_b128 v[214:217], v196 offset:37888
	ds_read_b128 v[218:221], v196 offset:38912
	ds_read_b128 v[222:225], v196 offset:39936
	global_load_lds_dwordx4 v[234:235], off
	v_lshl_add_u64 v[234:235], s[14:15], 0, v[158:159]
	s_mov_b32 m0, s52
	s_nop 0
	global_load_lds_dwordx4 v[234:235], off
	s_waitcnt vmcnt(8)
	s_waitcnt lgkmcnt(0)
	s_barrier
	s_waitcnt lgkmcnt(0)
	v_mfma_f32_16x16x32_bf16 v[124:127], v[128:131], v[172:175], v[124:127]
	v_mfma_f32_16x16x32_bf16 v[120:123], v[136:139], v[172:175], v[120:123]
	v_mfma_f32_16x16x32_bf16 v[108:111], v[128:131], v[202:205], v[108:111]
	v_mfma_f32_16x16x32_bf16 v[104:107], v[136:139], v[202:205], v[104:107]
	v_mfma_f32_16x16x32_bf16 v[92:95], v[128:131], v[210:213], v[92:95]
	v_mfma_f32_16x16x32_bf16 v[88:91], v[136:139], v[210:213], v[88:91]
	v_mfma_f32_16x16x32_bf16 v[76:79], v[128:131], v[218:221], v[76:79]
	v_mfma_f32_16x16x32_bf16 v[72:75], v[136:139], v[218:221], v[72:75]
	v_mfma_f32_16x16x32_bf16 v[124:127], v[132:135], v[198:201], v[124:127]
	v_mfma_f32_16x16x32_bf16 v[120:123], v[140:143], v[198:201], v[120:123]
	v_mfma_f32_16x16x32_bf16 v[108:111], v[132:135], v[206:209], v[108:111]
	v_mfma_f32_16x16x32_bf16 v[104:107], v[140:143], v[206:209], v[104:107]
	v_mfma_f32_16x16x32_bf16 v[92:95], v[132:135], v[214:217], v[92:95]
	v_mfma_f32_16x16x32_bf16 v[88:91], v[140:143], v[214:217], v[88:91]
	v_mfma_f32_16x16x32_bf16 v[76:79], v[132:135], v[222:225], v[76:79]
	v_mfma_f32_16x16x32_bf16 v[72:75], v[140:143], v[222:225], v[72:75]
	v_mfma_f32_16x16x32_bf16 v[116:119], v[144:147], v[172:175], v[116:119]
	v_mfma_f32_16x16x32_bf16 v[112:115], v[152:155], v[172:175], v[112:115]
	v_mfma_f32_16x16x32_bf16 v[100:103], v[144:147], v[202:205], v[100:103]
	v_mfma_f32_16x16x32_bf16 v[96:99], v[152:155], v[202:205], v[96:99]
	v_mfma_f32_16x16x32_bf16 v[84:87], v[144:147], v[210:213], v[84:87]
	v_mfma_f32_16x16x32_bf16 v[80:83], v[152:155], v[210:213], v[80:83]
	v_mfma_f32_16x16x32_bf16 v[68:71], v[144:147], v[218:221], v[68:71]
	v_mfma_f32_16x16x32_bf16 v[64:67], v[152:155], v[218:221], v[64:67]
	v_mfma_f32_16x16x32_bf16 v[116:119], v[148:151], v[198:201], v[116:119]
	v_mfma_f32_16x16x32_bf16 v[112:115], v[168:171], v[198:201], v[112:115]
	v_mfma_f32_16x16x32_bf16 v[100:103], v[148:151], v[206:209], v[100:103]
	v_mfma_f32_16x16x32_bf16 v[96:99], v[168:171], v[206:209], v[96:99]
	v_mfma_f32_16x16x32_bf16 v[84:87], v[148:151], v[214:217], v[84:87]
	v_mfma_f32_16x16x32_bf16 v[80:83], v[168:171], v[214:217], v[80:83]
	v_mfma_f32_16x16x32_bf16 v[68:71], v[148:151], v[222:225], v[68:71]
	v_mfma_f32_16x16x32_bf16 v[64:67], v[168:171], v[222:225], v[64:67]
	s_barrier
; #define PG8_STAGE(bufoff, gbase, voff) do { _Pragma("unroll") for (int _i = 0; _i < 2; ++_i) \
;         __builtin_amdgcn_global_load_lds((const unsigned*)((const char*)(gbase) + (voff)[_i]), (LAS unsigned*)(lds + (bufoff) + ldsw + _i * 8192), 16, 0, 0); } while (0)
; #define PG8_LDA(dst, b, h) do { _Pragma("unroll") for (int m = 0; m < 4; ++m) _Pragma("unroll") for (int k = 0; k < 2; ++k) dst[m][k] = *(const LAS bf16x8*)(lds + PG8_SA(b, h) + aoff + m * 2048 + k * 1024); } while (0)
; #define PG8_LDB(dst, b, h) do { _Pragma("unroll") for (int n = 0; n < 2; ++n) _Pragma("unroll") for (int k = 0; k < 2; ++k) dst[n][k] = *(const LAS bf16x8*)(lds + PG8_SB(b, h) + boff + n * 2048 + k * 1024); } while (0)
; #define PG8_WAIT_V(n) asm volatile("s_waitcnt vmcnt(" #n ")" ::: "memory")
; #define PG8_BAR __builtin_amdgcn_s_barrier()
; template <class Epi, class Sched>
; __device__ __forceinline__ void gemm_phase(LAS unsigned char* lds, const Gemm g, const Sched& S, const Epi& E) {
;     ...
;         for (int t = 0; t < nt; t += 2) {
;             const bool last = (t == nt - 2);
;             const char* a1 = cA + (size_t)(t + 1) * kstep;
;             const char* a2 = last ? nA : cA + (size_t)(t + 2) * kstep; const char* b2 = last ? nB : cB + (size_t)(t + 2) * kstep;
;             const char* a3 = a2 + kstep; const char* b3 = b2 + kstep;
;             PG8_LDB(B0, 0, 0); PG8_LDB(B1, 0, 1); PG8_SCHED; PG8_LDA(At, 0, 0); PG8_STAGE(PG8_SA(1, 1), a1 + hstepA, voffA);
;             PG8_WAIT_V(8); PG8_WAIT_L(0); PG8_BAR; PG8_MMA(0, 0, At, B0); PG8_MMA(0, 1, At, B1); PG8_BAR; PG8_SCHED;
;             PG8_LDA(At, 0, 1); PG8_STAGE(PG8_SB(0, 0), b2, voffB); PG8_STAGE(PG8_SB(0, 1), b2 + hstepB, voffB); PG8_STAGE(PG8_SA(0, 0), a2, voffA);
;             PG8_WAIT_V(8); PG8_WAIT_L(0); PG8_BAR; PG8_MMA(1, 0, At, B0); PG8_MMA(1, 1, At, B1); PG8_BAR; PG8_SCHED;
;             PG8_LDB(B0, 1, 0); PG8_LDB(B1, 1, 1); PG8_SCHED; PG8_LDA(At, 1, 0); PG8_STAGE(PG8_SA(0, 1), a2 + hstepA, voffA);
;             PG8_WAIT_V(8); PG8_WAIT_L(0); PG8_BAR; PG8_MMA(0, 0, At, B0); PG8_MMA(0, 1, At, B1); PG8_BAR; PG8_SCHED;
;             PG8_LDA(At, 1, 1); PG8_STAGE(PG8_SB(1, 0), b3, voffB); PG8_STAGE(PG8_SB(1, 1), b3 + hstepB, voffB); PG8_STAGE(PG8_SA(1, 0), a3, voffA);
;             PG8_WAIT_V(8); PG8_WAIT_L(0); PG8_BAR; PG8_MMA(1, 0, At, B0); PG8_MMA(1, 1, At, B1); PG8_BAR; PG8_SCHED;
;         }
	s_add_i32 s0, s0, s20
	v_lshl_add_u64 v[226:227], v[226:227], 0, s[30:31]
	s_mov_b32 m0, s0
	ds_read_b128 v[172:175], v196 offset:49152
	ds_read_b128 v[198:201], v196 offset:50176
	ds_read_b128 v[202:205], v196 offset:51200
	ds_read_b128 v[206:209], v196 offset:52224
	ds_read_b128 v[210:213], v196 offset:53248
	ds_read_b128 v[214:217], v196 offset:54272
	ds_read_b128 v[218:221], v196 offset:55296
	ds_read_b128 v[222:225], v196 offset:56320
	global_load_lds_dwordx4 v[226:227], off
	s_add_i32 m0, s0, 0x2000
	s_add_u32 s6, s6, 0xb0080
	v_lshl_add_u64 v[226:227], v[228:229], 0, s[30:31]
	s_addc_u32 s7, s7, 0
	s_add_i32 s0, s26, s20
	global_load_lds_dwordx4 v[226:227], off
	v_lshl_add_u64 v[226:227], s[6:7], 0, v[160:161]
	s_mov_b32 m0, s0
	s_nop 0
	global_load_lds_dwordx4 v[226:227], off
	v_lshl_add_u64 v[226:227], s[6:7], 0, v[162:163]
	s_add_i32 m0, s0, 0x2000
	s_nop 0
	global_load_lds_dwordx4 v[226:227], off
	v_lshl_add_u64 v[226:227], v[230:231], 0, s[30:31]
	s_mov_b32 m0, s24
	s_nop 0
	global_load_lds_dwordx4 v[226:227], off
	v_lshl_add_u64 v[226:227], v[232:233], 0, s[30:31]
	s_mov_b32 m0, s25
	s_nop 0
	global_load_lds_dwordx4 v[226:227], off
	s_waitcnt vmcnt(8)
	s_waitcnt lgkmcnt(0)
	s_barrier
	s_waitcnt lgkmcnt(0)
	v_mfma_f32_16x16x32_bf16 v[60:63], v[128:131], v[172:175], v[60:63]
	v_mfma_f32_16x16x32_bf16 v[56:59], v[136:139], v[172:175], v[56:59]
	v_mfma_f32_16x16x32_bf16 v[44:47], v[128:131], v[202:205], v[44:47]
	v_mfma_f32_16x16x32_bf16 v[40:43], v[136:139], v[202:205], v[40:43]
	v_mfma_f32_16x16x32_bf16 v[28:31], v[128:131], v[210:213], v[28:31]
	v_mfma_f32_16x16x32_bf16 v[24:27], v[136:139], v[210:213], v[24:27]
	v_mfma_f32_16x16x32_bf16 v[12:15], v[128:131], v[218:221], v[12:15]
	v_mfma_f32_16x16x32_bf16 v[8:11], v[136:139], v[218:221], v[8:11]
	v_mfma_f32_16x16x32_bf16 v[60:63], v[132:135], v[198:201], v[60:63]
	v_mfma_f32_16x16x32_bf16 v[56:59], v[140:143], v[198:201], v[56:59]
	v_mfma_f32_16x16x32_bf16 v[44:47], v[132:135], v[206:209], v[44:47]
	v_mfma_f32_16x16x32_bf16 v[40:43], v[140:143], v[206:209], v[40:43]
	v_mfma_f32_16x16x32_bf16 v[28:31], v[132:135], v[214:217], v[28:31]
	v_mfma_f32_16x16x32_bf16 v[24:27], v[140:143], v[214:217], v[24:27]
	v_mfma_f32_16x16x32_bf16 v[12:15], v[132:135], v[222:225], v[12:15]
	v_mfma_f32_16x16x32_bf16 v[8:11], v[140:143], v[222:225], v[8:11]
	v_mfma_f32_16x16x32_bf16 v[52:55], v[144:147], v[172:175], v[52:55]
	v_mfma_f32_16x16x32_bf16 v[48:51], v[152:155], v[172:175], v[48:51]
	v_mfma_f32_16x16x32_bf16 v[36:39], v[144:147], v[202:205], v[36:39]
	v_mfma_f32_16x16x32_bf16 v[32:35], v[152:155], v[202:205], v[32:35]
	v_mfma_f32_16x16x32_bf16 v[20:23], v[144:147], v[210:213], v[20:23]
	v_mfma_f32_16x16x32_bf16 v[16:19], v[152:155], v[210:213], v[16:19]
	v_mfma_f32_16x16x32_bf16 v[4:7], v[144:147], v[218:221], v[4:7]
	v_mfma_f32_16x16x32_bf16 v[0:3], v[152:155], v[218:221], v[0:3]
	v_mfma_f32_16x16x32_bf16 v[52:55], v[148:151], v[198:201], v[52:55]
	v_mfma_f32_16x16x32_bf16 v[48:51], v[168:171], v[198:201], v[48:51]
	v_mfma_f32_16x16x32_bf16 v[36:39], v[148:151], v[206:209], v[36:39]
	v_mfma_f32_16x16x32_bf16 v[32:35], v[168:171], v[206:209], v[32:35]
	v_mfma_f32_16x16x32_bf16 v[20:23], v[148:151], v[214:217], v[20:23]
	v_mfma_f32_16x16x32_bf16 v[16:19], v[168:171], v[214:217], v[16:19]
	v_mfma_f32_16x16x32_bf16 v[4:7], v[148:151], v[222:225], v[4:7]
	v_mfma_f32_16x16x32_bf16 v[0:3], v[168:171], v[222:225], v[0:3]
	s_barrier
	s_add_i32 s54, s54, 2
	s_add_u32 s33, s33, 0x100
	s_addc_u32 s53, s53, 0
	s_cmp_gt_u32 s54, 41
	s_mov_b64 s[44:45], s[46:47]
.LBB0_807:
	s_add_u32 s46, s44, 0x100
	s_addc_u32 s47, s45, 0
	s_add_i32 s0, 0, 0x10000
	s_cmp_eq_u32 s54, 40
	s_cselect_b32 s15, s23, s47
	s_cselect_b32 s14, s22, s46
	s_cselect_b32 s7, s35, s53
	s_cselect_b32 s6, s34, s33
	s_add_i32 s26, 0, 0x14000
	v_add_u32_e32 v140, s0, v186
	v_add_u32_e32 v168, s26, v186
	ds_read_b128 v[128:131], v140
	ds_read_b128 v[132:135], v140 offset:1024
	ds_read_b128 v[136:139], v140 offset:2048
	ds_read_b128 v[140:143], v140 offset:3072
	ds_read_b128 v[144:147], v168
	ds_read_b128 v[148:151], v168 offset:1024
	ds_read_b128 v[152:155], v168 offset:2048
	ds_read_b128 v[168:171], v168 offset:3072
	v_lshl_add_u64 v[226:227], s[44:45], 0, v[164:165]
	s_add_i32 m0, s49, 0xc000
	ds_read_b128 v[172:175], v196
	ds_read_b128 v[198:201], v196 offset:1024
	ds_read_b128 v[202:205], v196 offset:2048
	ds_read_b128 v[206:209], v196 offset:3072
	ds_read_b128 v[210:213], v196 offset:4096
	ds_read_b128 v[214:217], v196 offset:5120
	ds_read_b128 v[218:221], v196 offset:6144
	ds_read_b128 v[222:225], v196 offset:7168
	global_load_lds_dwordx4 v[226:227], off
	v_lshl_add_u64 v[226:227], s[44:45], 0, v[166:167]
	s_add_i32 m0, s49, 0xe000
	s_nop 0
	global_load_lds_dwordx4 v[226:227], off
	s_waitcnt vmcnt(8)
	s_waitcnt lgkmcnt(0)
	s_barrier
; #define PG8_STAGE(bufoff, gbase, voff) do { _Pragma("unroll") for (int _i = 0; _i < 2; ++_i) \
;         __builtin_amdgcn_global_load_lds((const unsigned*)((const char*)(gbase) + (voff)[_i]), (LAS unsigned*)(lds + (bufoff) + ldsw + _i * 8192), 16, 0, 0); } while (0)
; #define PG8_LDA(dst, b, h) do { _Pragma("unroll") for (int m = 0; m < 4; ++m) _Pragma("unroll") for (int k = 0; k < 2; ++k) dst[m][k] = *(const LAS bf16x8*)(lds + PG8_SA(b, h) + aoff + m * 2048 + k * 1024); } while (0)
; #define PG8_LDB(dst, b, h) do { _Pragma("unroll") for (int n = 0; n < 2; ++n) _Pragma("unroll") for (int k = 0; k < 2; ++k) dst[n][k] = *(const LAS bf16x8*)(lds + PG8_SB(b, h) + boff + n * 2048 + k * 1024); } while (0)
; #define PG8_MMA(ai, bj, At, Bt) do { __builtin_amdgcn_s_setprio(1); _Pragma("unroll") for (int m = 0; m < 4; ++m) _Pragma("unroll") for (int n = 0; n < 2; ++n) _Pragma("unroll") for (int k = 0; k < 2; ++k) \
;         acc[ai][bj][m][n] = __builtin_amdgcn_mfma_f32_16x16x32_bf16(Bt[n][k], At[m][k], acc[ai][bj][m][n], 0, 0, 0); __builtin_amdgcn_s_setprio(0); } while (0)
; #define PG8_WAIT_V(n) asm volatile("s_waitcnt vmcnt(" #n ")" ::: "memory")
; #define PG8_WAIT_L(n) asm volatile("s_waitcnt lgkmcnt(" #n ")" ::: "memory")
; #define PG8_BAR __builtin_amdgcn_s_barrier()
; #define PG8_SCHED __builtin_amdgcn_sched_barrier(0)
; template <class Epi, class Sched>
; __device__ __forceinline__ void gemm_phase(LAS unsigned char* lds, const Gemm g, const Sched& S, const Epi& E) {
;     ...
;             PG8_WAIT_V(8); PG8_WAIT_L(0); PG8_BAR; PG8_MMA(0, 0, At, B0); PG8_MMA(0, 1, At, B1); PG8_BAR; PG8_SCHED;
;             PG8_LDA(At, 0, 1); PG8_STAGE(PG8_SB(0, 0), b2, voffB); PG8_STAGE(PG8_SB(0, 1), b2 + hstepB, voffB); PG8_STAGE(PG8_SA(0, 0), a2, voffA);
;             PG8_WAIT_V(8); PG8_WAIT_L(0); PG8_BAR; PG8_MMA(1, 0, At, B0); PG8_MMA(1, 1, At, B1); PG8_BAR; PG8_SCHED;
;             PG8_LDB(B0, 1, 0); PG8_LDB(B1, 1, 1); PG8_SCHED; PG8_LDA(At, 1, 0); PG8_STAGE(PG8_SA(0, 1), a2 + hstepA, voffA);
;             PG8_WAIT_V(8); PG8_WAIT_L(0); PG8_BAR; PG8_MMA(0, 0, At, B0); PG8_MMA(0, 1, At, B1); PG8_BAR; PG8_SCHED;
	s_waitcnt lgkmcnt(0)
	v_mfma_f32_16x16x32_bf16 v[124:127], v[128:131], v[172:175], v[124:127]
	v_mfma_f32_16x16x32_bf16 v[120:123], v[136:139], v[172:175], v[120:123]
	v_mfma_f32_16x16x32_bf16 v[108:111], v[128:131], v[202:205], v[108:111]
	v_mfma_f32_16x16x32_bf16 v[104:107], v[136:139], v[202:205], v[104:107]
	v_mfma_f32_16x16x32_bf16 v[92:95], v[128:131], v[210:213], v[92:95]
	v_mfma_f32_16x16x32_bf16 v[88:91], v[136:139], v[210:213], v[88:91]
	v_mfma_f32_16x16x32_bf16 v[76:79], v[128:131], v[218:221], v[76:79]
	v_mfma_f32_16x16x32_bf16 v[72:75], v[136:139], v[218:221], v[72:75]
	v_mfma_f32_16x16x32_bf16 v[124:127], v[132:135], v[198:201], v[124:127]
	v_mfma_f32_16x16x32_bf16 v[120:123], v[140:143], v[198:201], v[120:123]
	v_mfma_f32_16x16x32_bf16 v[108:111], v[132:135], v[206:209], v[108:111]
	v_mfma_f32_16x16x32_bf16 v[104:107], v[140:143], v[206:209], v[104:107]
	v_mfma_f32_16x16x32_bf16 v[92:95], v[132:135], v[214:217], v[92:95]
	v_mfma_f32_16x16x32_bf16 v[88:91], v[140:143], v[214:217], v[88:91]
	v_mfma_f32_16x16x32_bf16 v[76:79], v[132:135], v[222:225], v[76:79]
	v_mfma_f32_16x16x32_bf16 v[72:75], v[140:143], v[222:225], v[72:75]
	v_mfma_f32_16x16x32_bf16 v[116:119], v[144:147], v[172:175], v[116:119]
	v_mfma_f32_16x16x32_bf16 v[112:115], v[152:155], v[172:175], v[112:115]
	v_mfma_f32_16x16x32_bf16 v[100:103], v[144:147], v[202:205], v[100:103]
	v_mfma_f32_16x16x32_bf16 v[96:99], v[152:155], v[202:205], v[96:99]
	v_mfma_f32_16x16x32_bf16 v[84:87], v[144:147], v[210:213], v[84:87]
	v_mfma_f32_16x16x32_bf16 v[80:83], v[152:155], v[210:213], v[80:83]
	v_mfma_f32_16x16x32_bf16 v[68:71], v[144:147], v[218:221], v[68:71]
	v_mfma_f32_16x16x32_bf16 v[64:67], v[152:155], v[218:221], v[64:67]
	v_mfma_f32_16x16x32_bf16 v[116:119], v[148:151], v[198:201], v[116:119]
	v_mfma_f32_16x16x32_bf16 v[112:115], v[168:171], v[198:201], v[112:115]
	v_mfma_f32_16x16x32_bf16 v[100:103], v[148:151], v[206:209], v[100:103]
	v_mfma_f32_16x16x32_bf16 v[96:99], v[168:171], v[206:209], v[96:99]
	v_mfma_f32_16x16x32_bf16 v[84:87], v[148:151], v[214:217], v[84:87]
	v_mfma_f32_16x16x32_bf16 v[80:83], v[168:171], v[214:217], v[80:83]
	v_mfma_f32_16x16x32_bf16 v[68:71], v[148:151], v[222:225], v[68:71]
	v_mfma_f32_16x16x32_bf16 v[64:67], v[168:171], v[222:225], v[64:67]
	s_barrier
	s_add_i32 s0, s0, s20
	v_lshl_add_u64 v[226:227], s[6:7], 0, v[160:161]
	s_mov_b32 m0, s0
	ds_read_b128 v[172:175], v196 offset:16384
	ds_read_b128 v[198:201], v196 offset:17408
	ds_read_b128 v[202:205], v196 offset:18432
	ds_read_b128 v[206:209], v196 offset:19456
	ds_read_b128 v[210:213], v196 offset:20480
	ds_read_b128 v[214:217], v196 offset:21504
	ds_read_b128 v[218:221], v196 offset:22528
	ds_read_b128 v[222:225], v196 offset:23552
	global_load_lds_dwordx4 v[226:227], off
	s_add_i32 m0, s0, 0x2000
	s_add_u32 s44, s6, 0xb0000
	v_lshl_add_u64 v[228:229], s[6:7], 0, v[162:163]
	s_addc_u32 s45, s7, 0
	s_add_i32 s0, s26, s20
	global_load_lds_dwordx4 v[228:229], off
	v_lshl_add_u64 v[230:231], s[44:45], 0, v[160:161]
	s_mov_b32 m0, s0
	v_lshl_add_u64 v[232:233], s[14:15], 0, v[158:159]
	global_load_lds_dwordx4 v[230:231], off
	v_lshl_add_u64 v[230:231], s[44:45], 0, v[162:163]
	s_add_i32 m0, s0, 0x2000
	s_nop 0
	global_load_lds_dwordx4 v[230:231], off
	v_lshl_add_u64 v[230:231], s[14:15], 0, v[156:157]
	s_mov_b32 m0, s49
	s_nop 0
	global_load_lds_dwordx4 v[230:231], off
	s_mov_b32 m0, s50
	s_nop 0
	global_load_lds_dwordx4 v[232:233], off
	s_waitcnt vmcnt(8)
	s_waitcnt lgkmcnt(0)
	s_barrier
	s_waitcnt lgkmcnt(0)
	v_mfma_f32_16x16x32_bf16 v[60:63], v[128:131], v[172:175], v[60:63]
	v_mfma_f32_16x16x32_bf16 v[56:59], v[136:139], v[172:175], v[56:59]
	v_mfma_f32_16x16x32_bf16 v[44:47], v[128:131], v[202:205], v[44:47]
	v_mfma_f32_16x16x32_bf16 v[40:43], v[136:139], v[202:205], v[40:43]
	v_mfma_f32_16x16x32_bf16 v[28:31], v[128:131], v[210:213], v[28:31]
	v_mfma_f32_16x16x32_bf16 v[24:27], v[136:139], v[210:213], v[24:27]
	v_mfma_f32_16x16x32_bf16 v[12:15], v[128:131], v[218:221], v[12:15]
	v_mfma_f32_16x16x32_bf16 v[8:11], v[136:139], v[218:221], v[8:11]
	v_mfma_f32_16x16x32_bf16 v[60:63], v[132:135], v[198:201], v[60:63]
	v_mfma_f32_16x16x32_bf16 v[56:59], v[140:143], v[198:201], v[56:59]
	v_mfma_f32_16x16x32_bf16 v[44:47], v[132:135], v[206:209], v[44:47]
	v_mfma_f32_16x16x32_bf16 v[40:43], v[140:143], v[206:209], v[40:43]
	v_mfma_f32_16x16x32_bf16 v[28:31], v[132:135], v[214:217], v[28:31]
	v_mfma_f32_16x16x32_bf16 v[24:27], v[140:143], v[214:217], v[24:27]
	v_mfma_f32_16x16x32_bf16 v[12:15], v[132:135], v[222:225], v[12:15]
	v_mfma_f32_16x16x32_bf16 v[8:11], v[140:143], v[222:225], v[8:11]
	v_mfma_f32_16x16x32_bf16 v[52:55], v[144:147], v[172:175], v[52:55]
	v_mfma_f32_16x16x32_bf16 v[48:51], v[152:155], v[172:175], v[48:51]
	v_mfma_f32_16x16x32_bf16 v[36:39], v[144:147], v[202:205], v[36:39]
	v_mfma_f32_16x16x32_bf16 v[32:35], v[152:155], v[202:205], v[32:35]
	v_mfma_f32_16x16x32_bf16 v[20:23], v[144:147], v[210:213], v[20:23]
	v_mfma_f32_16x16x32_bf16 v[16:19], v[152:155], v[210:213], v[16:19]
	v_mfma_f32_16x16x32_bf16 v[4:7], v[144:147], v[218:221], v[4:7]
	v_mfma_f32_16x16x32_bf16 v[0:3], v[152:155], v[218:221], v[0:3]
	v_mfma_f32_16x16x32_bf16 v[52:55], v[148:151], v[198:201], v[52:55]
	v_mfma_f32_16x16x32_bf16 v[48:51], v[168:171], v[198:201], v[48:51]
	v_mfma_f32_16x16x32_bf16 v[36:39], v[148:151], v[206:209], v[36:39]
	v_mfma_f32_16x16x32_bf16 v[32:35], v[168:171], v[206:209], v[32:35]
	v_mfma_f32_16x16x32_bf16 v[20:23], v[148:151], v[214:217], v[20:23]
	v_mfma_f32_16x16x32_bf16 v[16:19], v[168:171], v[214:217], v[16:19]
	v_mfma_f32_16x16x32_bf16 v[4:7], v[148:151], v[222:225], v[4:7]
	v_mfma_f32_16x16x32_bf16 v[0:3], v[168:171], v[222:225], v[0:3]
	s_barrier
; #define PG8_STAGE(bufoff, gbase, voff) do { _Pragma("unroll") for (int _i = 0; _i < 2; ++_i) \
;         __builtin_amdgcn_global_load_lds((const unsigned*)((const char*)(gbase) + (voff)[_i]), (LAS unsigned*)(lds + (bufoff) + ldsw + _i * 8192), 16, 0, 0); } while (0)
; #define PG8_LDA(dst, b, h) do { _Pragma("unroll") for (int m = 0; m < 4; ++m) _Pragma("unroll") for (int k = 0; k < 2; ++k) dst[m][k] = *(const LAS bf16x8*)(lds + PG8_SA(b, h) + aoff + m * 2048 + k * 1024); } while (0)
; #define PG8_LDB(dst, b, h) do { _Pragma("unroll") for (int n = 0; n < 2; ++n) _Pragma("unroll") for (int k = 0; k < 2; ++k) dst[n][k] = *(const LAS bf16x8*)(lds + PG8_SB(b, h) + boff + n * 2048 + k * 1024); } while (0)
; #define PG8_MMA(ai, bj, At, Bt) do { __builtin_amdgcn_s_setprio(1); _Pragma("unroll") for (int m = 0; m < 4; ++m) _Pragma("unroll") for (int n = 0; n < 2; ++n) _Pragma("unroll") for (int k = 0; k < 2; ++k) \
;         acc[ai][bj][m][n] = __builtin_amdgcn_mfma_f32_16x16x32_bf16(Bt[n][k], At[m][k], acc[ai][bj][m][n], 0, 0, 0); __builtin_amdgcn_s_setprio(0); } while (0)
; #define PG8_WAIT_V(n) asm volatile("s_waitcnt vmcnt(" #n ")" ::: "memory")
; #define PG8_WAIT_L(n) asm volatile("s_waitcnt lgkmcnt(" #n ")" ::: "memory")
; #define PG8_BAR __builtin_amdgcn_s_barrier()
; #define PG8_SCHED __builtin_amdgcn_sched_barrier(0)
; template <class Epi, class Sched>
; __device__ __forceinline__ void gemm_phase(LAS unsigned char* lds, const Gemm g, const Sched& S, const Epi& E) {
;     ...
;             PG8_LDB(B0, 1, 0); PG8_LDB(B1, 1, 1); PG8_SCHED; PG8_LDA(At, 1, 0); PG8_STAGE(PG8_SA(0, 1), a2 + hstepA, voffA);
;             PG8_WAIT_V(8); PG8_WAIT_L(0); PG8_BAR; PG8_MMA(0, 0, At, B0); PG8_MMA(0, 1, At, B1); PG8_BAR; PG8_SCHED;
	s_add_i32 s0, 0, 0x18000
	s_add_i32 s26, 0, 0x1c000
	v_add_u32_e32 v140, s0, v186
	v_add_u32_e32 v168, s26, v186
	ds_read_b128 v[128:131], v140
	ds_read_b128 v[132:135], v140 offset:1024
	ds_read_b128 v[136:139], v140 offset:2048
	ds_read_b128 v[140:143], v140 offset:3072
	ds_read_b128 v[144:147], v168
	ds_read_b128 v[148:151], v168 offset:1024
	ds_read_b128 v[152:155], v168 offset:2048
	ds_read_b128 v[168:171], v168 offset:3072
	s_add_u32 s14, s14, 0xb0000
	s_addc_u32 s15, s15, 0
	s_mov_b32 m0, s51
	v_lshl_add_u64 v[234:235], s[14:15], 0, v[156:157]
	ds_read_b128 v[172:175], v196 offset:32768
	ds_read_b128 v[198:201], v196 offset:33792
	ds_read_b128 v[202:205], v196 offset:34816
	ds_read_b128 v[206:209], v196 offset:35840
	ds_read_b128 v[210:213], v196 offset:36864
	ds_read_b128 v[214:217], v196 offset:37888
	ds_read_b128 v[218:221], v196 offset:38912
	ds_read_b128 v[222:225], v196 offset:39936
	global_load_lds_dwordx4 v[234:235], off
	v_lshl_add_u64 v[234:235], s[14:15], 0, v[158:159]
	s_mov_b32 m0, s52
	s_nop 0
	global_load_lds_dwordx4 v[234:235], off
	s_waitcnt vmcnt(8)
	s_waitcnt lgkmcnt(0)
	s_barrier
	s_waitcnt lgkmcnt(0)
	v_mfma_f32_16x16x32_bf16 v[124:127], v[128:131], v[172:175], v[124:127]
	v_mfma_f32_16x16x32_bf16 v[120:123], v[136:139], v[172:175], v[120:123]
	v_mfma_f32_16x16x32_bf16 v[108:111], v[128:131], v[202:205], v[108:111]
	v_mfma_f32_16x16x32_bf16 v[104:107], v[136:139], v[202:205], v[104:107]
	v_mfma_f32_16x16x32_bf16 v[92:95], v[128:131], v[210:213], v[92:95]
	v_mfma_f32_16x16x32_bf16 v[88:91], v[136:139], v[210:213], v[88:91]
	v_mfma_f32_16x16x32_bf16 v[76:79], v[128:131], v[218:221], v[76:79]
	v_mfma_f32_16x16x32_bf16 v[72:75], v[136:139], v[218:221], v[72:75]
	v_mfma_f32_16x16x32_bf16 v[124:127], v[132:135], v[198:201], v[124:127]
	v_mfma_f32_16x16x32_bf16 v[120:123], v[140:143], v[198:201], v[120:123]
	v_mfma_f32_16x16x32_bf16 v[108:111], v[132:135], v[206:209], v[108:111]
	v_mfma_f32_16x16x32_bf16 v[104:107], v[140:143], v[206:209], v[104:107]
	v_mfma_f32_16x16x32_bf16 v[92:95], v[132:135], v[214:217], v[92:95]
	v_mfma_f32_16x16x32_bf16 v[88:91], v[140:143], v[214:217], v[88:91]
	v_mfma_f32_16x16x32_bf16 v[76:79], v[132:135], v[222:225], v[76:79]
	v_mfma_f32_16x16x32_bf16 v[72:75], v[140:143], v[222:225], v[72:75]
	v_mfma_f32_16x16x32_bf16 v[116:119], v[144:147], v[172:175], v[116:119]
	v_mfma_f32_16x16x32_bf16 v[112:115], v[152:155], v[172:175], v[112:115]
	v_mfma_f32_16x16x32_bf16 v[100:103], v[144:147], v[202:205], v[100:103]
	v_mfma_f32_16x16x32_bf16 v[96:99], v[152:155], v[202:205], v[96:99]
	v_mfma_f32_16x16x32_bf16 v[84:87], v[144:147], v[210:213], v[84:87]
	v_mfma_f32_16x16x32_bf16 v[80:83], v[152:155], v[210:213], v[80:83]
	v_mfma_f32_16x16x32_bf16 v[68:71], v[144:147], v[218:221], v[68:71]
	v_mfma_f32_16x16x32_bf16 v[64:67], v[152:155], v[218:221], v[64:67]
	v_mfma_f32_16x16x32_bf16 v[116:119], v[148:151], v[198:201], v[116:119]
	v_mfma_f32_16x16x32_bf16 v[112:115], v[168:171], v[198:201], v[112:115]
	v_mfma_f32_16x16x32_bf16 v[100:103], v[148:151], v[206:209], v[100:103]
	v_mfma_f32_16x16x32_bf16 v[96:99], v[168:171], v[206:209], v[96:99]
	v_mfma_f32_16x16x32_bf16 v[84:87], v[148:151], v[214:217], v[84:87]
	v_mfma_f32_16x16x32_bf16 v[80:83], v[168:171], v[214:217], v[80:83]
	v_mfma_f32_16x16x32_bf16 v[68:71], v[148:151], v[222:225], v[68:71]
	v_mfma_f32_16x16x32_bf16 v[64:67], v[168:171], v[222:225], v[64:67]
	s_barrier
; #define PG8_STAGE(bufoff, gbase, voff) do { _Pragma("unroll") for (int _i = 0; _i < 2; ++_i) \
;         __builtin_amdgcn_global_load_lds((const unsigned*)((const char*)(gbase) + (voff)[_i]), (LAS unsigned*)(lds + (bufoff) + ldsw + _i * 8192), 16, 0, 0); } while (0)
; #define PG8_LDA(dst, b, h) do { _Pragma("unroll") for (int m = 0; m < 4; ++m) _Pragma("unroll") for (int k = 0; k < 2; ++k) dst[m][k] = *(const LAS bf16x8*)(lds + PG8_SA(b, h) + aoff + m * 2048 + k * 1024); } while (0)
; #define PG8_MMA(ai, bj, At, Bt) do { __builtin_amdgcn_s_setprio(1); _Pragma("unroll") for (int m = 0; m < 4; ++m) _Pragma("unroll") for (int n = 0; n < 2; ++n) _Pragma("unroll") for (int k = 0; k < 2; ++k) \
;         acc[ai][bj][m][n] = __builtin_amdgcn_mfma_f32_16x16x32_bf16(Bt[n][k], At[m][k], acc[ai][bj][m][n], 0, 0, 0); __builtin_amdgcn_s_setprio(0); } while (0)
; #define PG8_WAIT_V(n) asm volatile("s_waitcnt vmcnt(" #n ")" ::: "memory")
; #define PG8_WAIT_L(n) asm volatile("s_waitcnt lgkmcnt(" #n ")" ::: "memory")
; #define PG8_BAR __builtin_amdgcn_s_barrier()
; #define PG8_SCHED __builtin_amdgcn_sched_barrier(0)
; template <class Epi, class Sched>
; __device__ __forceinline__ void gemm_phase(LAS unsigned char* lds, const Gemm g, const Sched& S, const Epi& E) {
;     ...
;             PG8_LDA(At, 1, 1); PG8_STAGE(PG8_SB(1, 0), b3, voffB); PG8_STAGE(PG8_SB(1, 1), b3 + hstepB, voffB); PG8_STAGE(PG8_SA(1, 0), a3, voffA);
;             PG8_WAIT_V(8); PG8_WAIT_L(0); PG8_BAR; PG8_MMA(1, 0, At, B0); PG8_MMA(1, 1, At, B1); PG8_BAR; PG8_SCHED;
;         }
;         if (wr == 0) PG8_BAR;
	s_add_i32 s0, s0, s20
	v_lshl_add_u64 v[226:227], v[226:227], 0, s[30:31]
	s_mov_b32 m0, s0
	ds_read_b128 v[172:175], v196 offset:49152
	ds_read_b128 v[198:201], v196 offset:50176
	ds_read_b128 v[202:205], v196 offset:51200
	ds_read_b128 v[206:209], v196 offset:52224
	ds_read_b128 v[210:213], v196 offset:53248
	ds_read_b128 v[214:217], v196 offset:54272
	ds_read_b128 v[218:221], v196 offset:55296
	ds_read_b128 v[222:225], v196 offset:56320
	global_load_lds_dwordx4 v[226:227], off
	s_add_i32 m0, s0, 0x2000
	s_add_u32 s6, s6, 0xb0080
	v_lshl_add_u64 v[226:227], v[228:229], 0, s[30:31]
	s_addc_u32 s7, s7, 0
	s_add_i32 s0, s26, s20
	global_load_lds_dwordx4 v[226:227], off
	v_lshl_add_u64 v[226:227], s[6:7], 0, v[160:161]
	s_mov_b32 m0, s0
	s_nop 0
	global_load_lds_dwordx4 v[226:227], off
	v_lshl_add_u64 v[226:227], s[6:7], 0, v[162:163]
	s_add_i32 m0, s0, 0x2000
	s_nop 0
	global_load_lds_dwordx4 v[226:227], off
	v_lshl_add_u64 v[226:227], v[230:231], 0, s[30:31]
	s_mov_b32 m0, s24
	s_nop 0
	global_load_lds_dwordx4 v[226:227], off
	v_lshl_add_u64 v[226:227], v[232:233], 0, s[30:31]
	s_mov_b32 m0, s25
	s_nop 0
	global_load_lds_dwordx4 v[226:227], off
	s_waitcnt vmcnt(8)
	s_waitcnt lgkmcnt(0)
	s_barrier
	s_waitcnt lgkmcnt(0)
	v_mfma_f32_16x16x32_bf16 v[60:63], v[128:131], v[172:175], v[60:63]
	v_mfma_f32_16x16x32_bf16 v[56:59], v[136:139], v[172:175], v[56:59]
	v_mfma_f32_16x16x32_bf16 v[44:47], v[128:131], v[202:205], v[44:47]
	v_mfma_f32_16x16x32_bf16 v[40:43], v[136:139], v[202:205], v[40:43]
	v_mfma_f32_16x16x32_bf16 v[28:31], v[128:131], v[210:213], v[28:31]
	v_mfma_f32_16x16x32_bf16 v[24:27], v[136:139], v[210:213], v[24:27]
	v_mfma_f32_16x16x32_bf16 v[12:15], v[128:131], v[218:221], v[12:15]
	v_mfma_f32_16x16x32_bf16 v[8:11], v[136:139], v[218:221], v[8:11]
	v_mfma_f32_16x16x32_bf16 v[60:63], v[132:135], v[198:201], v[60:63]
	v_mfma_f32_16x16x32_bf16 v[56:59], v[140:143], v[198:201], v[56:59]
	v_mfma_f32_16x16x32_bf16 v[44:47], v[132:135], v[206:209], v[44:47]
	v_mfma_f32_16x16x32_bf16 v[40:43], v[140:143], v[206:209], v[40:43]
	v_mfma_f32_16x16x32_bf16 v[28:31], v[132:135], v[214:217], v[28:31]
	v_mfma_f32_16x16x32_bf16 v[24:27], v[140:143], v[214:217], v[24:27]
	v_mfma_f32_16x16x32_bf16 v[12:15], v[132:135], v[222:225], v[12:15]
	v_mfma_f32_16x16x32_bf16 v[8:11], v[140:143], v[222:225], v[8:11]
	v_mfma_f32_16x16x32_bf16 v[52:55], v[144:147], v[172:175], v[52:55]
	v_mfma_f32_16x16x32_bf16 v[48:51], v[152:155], v[172:175], v[48:51]
	v_mfma_f32_16x16x32_bf16 v[36:39], v[144:147], v[202:205], v[36:39]
	v_mfma_f32_16x16x32_bf16 v[32:35], v[152:155], v[202:205], v[32:35]
	v_mfma_f32_16x16x32_bf16 v[20:23], v[144:147], v[210:213], v[20:23]
	v_mfma_f32_16x16x32_bf16 v[16:19], v[152:155], v[210:213], v[16:19]
	v_mfma_f32_16x16x32_bf16 v[4:7], v[144:147], v[218:221], v[4:7]
	v_mfma_f32_16x16x32_bf16 v[0:3], v[152:155], v[218:221], v[0:3]
	v_mfma_f32_16x16x32_bf16 v[52:55], v[148:151], v[198:201], v[52:55]
	v_mfma_f32_16x16x32_bf16 v[48:51], v[168:171], v[198:201], v[48:51]
	v_mfma_f32_16x16x32_bf16 v[36:39], v[148:151], v[206:209], v[36:39]
	v_mfma_f32_16x16x32_bf16 v[32:35], v[168:171], v[206:209], v[32:35]
	v_mfma_f32_16x16x32_bf16 v[20:23], v[148:151], v[214:217], v[20:23]
	v_mfma_f32_16x16x32_bf16 v[16:19], v[168:171], v[214:217], v[16:19]
	v_mfma_f32_16x16x32_bf16 v[4:7], v[148:151], v[222:225], v[4:7]
	v_mfma_f32_16x16x32_bf16 v[0:3], v[168:171], v[222:225], v[0:3]
	s_barrier
	s_add_i32 s54, s54, 2
	s_add_u32 s33, s33, 0x100
	s_addc_u32 s53, s53, 0
	s_cmp_gt_u32 s54, 41
	s_mov_b64 s[44:45], s[46:47]
	s_cbranch_scc0 .LBB0_807
	s_setprio 0
	s_and_b64 vcc, exec, s[18:19]
	s_cbranch_vccz .LBB0_810
	s_barrier
